# sse2 + As[1][1] of the next unit's K-tile 1 staged at the epilogue start (ahead of the stores) so the first three vmcnt waits of a follow-on unit are skipped (more store-drain overlap)
# baseline (speedup 1.0000x reference)
; #define PG8_STAGE(bufoff, gbase, voff) do { _Pragma("unroll") for (int _i = 0; _i < 2; ++_i) \
;         __builtin_amdgcn_global_load_lds((const unsigned*)((const char*)(gbase) + (size_t)_i * qstep + (voff)[0]), (PG8_LAS unsigned*)(lds + (bufoff) + ldsw + _i * 8192), 16, 0, 0); } while (0)
; #define PG8_LDA(dst, b, h) do { _Pragma("unroll") for (int m = 0; m < 4; ++m) _Pragma("unroll") for (int k = 0; k < 2; ++k) dst[m][k] = *(const PG8_LAS bf16x8*)(lds + PG8_SA(b, h) + aoff + m * 2048 + k * 1024); } while (0)
; #define PG8_LDB(dst, b, h) do { _Pragma("unroll") for (int n = 0; n < 2; ++n) _Pragma("unroll") for (int k = 0; k < 2; ++k) dst[n][k] = *(const PG8_LAS bf16x8*)(lds + PG8_SB(b, h) + boff + n * 2048 + k * 1024); } while (0)
; #define PG8_MMA(ai, bj, At, Bt) do { __builtin_amdgcn_s_setprio(1); _Pragma("unroll") for (int m = 0; m < 4; ++m) _Pragma("unroll") for (int n = 0; n < 2; ++n) _Pragma("unroll") for (int k = 0; k < 2; ++k) \
;         acc[ai][bj][m][n] = __builtin_amdgcn_mfma_f32_16x16x32_bf16(Bt[n][k], At[m][k], acc[ai][bj][m][n], 0, 0, 0); __builtin_amdgcn_s_setprio(0); } while (0)
; #define PG8_WAIT_V89() do { if constexpr (SLIVER) PG8_WAIT_V(9); else PG8_WAIT_V(8); } while (0)
; #define PG8_WAIT_L(n) asm volatile("s_waitcnt lgkmcnt(" #n ")" ::: "memory")
; #define PG8_BAR __builtin_amdgcn_s_barrier()
; #define PG8_SCHED __builtin_amdgcn_sched_barrier(0)
; template <class Epi, class Sched, bool ALIGN_EPI = false, bool SP2 = false, bool SLIVER = false>
; __device__ __forceinline__ void gemm_phase(PG8_LAS unsigned char* lds, const Gemm g, const Sched& S, const Epi& E) {
;     ...
;             const bool last = (t == nt - 2);
;             const char* a1 = cA + (size_t)(t + 1) * kstep;
;             const char* a2 = last ? nA : cA + (size_t)(t + 2) * kstep; const char* b2 = last ? nB : cB + (size_t)(t + 2) * kstep;
;             const char* a3 = a2 + kstep; const char* b3 = b2 + kstep;
;             const char* s1 = cS + (size_t)(t + 1) * kstep; const char* s2 = last ? nS : cS + (size_t)(t + 2) * kstep;
;             if (last && has_next) S.a_ready(nxt);
;             if constexpr (SP2) {
;             PG8_LDB(B0, 0, 0); PG8_LDB(B1, 0, 1); PG8_SCHED; PG8_LDA(At, 0, 0); PG8_STAGE(PG8_SA(1, 1), a1 + hstep, voffA); PG8_STAGE_S(1, s1);
;             PG8_WAIT_V89(); PG8_WAIT_L(0); PG8_BAR; PG8_MMA(0, 0, At, B0); PG8_MMA(0, 1, At, B1); PG8_BAR; PG8_SCHED;
.LBB0_153:
	s_add_u32 s62, s40, 0xfff80080
	s_addc_u32 s63, s41, -1
	s_add_i32 s77, 0, 0x10000
	s_cmp_eq_u32 s76, 28
	s_cselect_b32 s63, s12, s63
	s_cselect_b32 s62, s13, s62
	v_add_u32_e32 v144, s77, v145
	s_cselect_b32 s79, s66, s69
	s_cselect_b32 s78, s67, s68
	s_add_i32 s80, 0, 0x14000
	ds_read_b128 v[136:139], v144
	ds_read_b128 v[140:143], v144 offset:1024
	ds_read_b128 v[150:153], v144 offset:2048
	ds_read_b128 v[154:157], v144 offset:3072
	v_add_u32_e32 v144, s80, v145
	ds_read_b128 v[158:161], v144
	ds_read_b128 v[162:165], v144 offset:1024
	ds_read_b128 v[166:169], v144 offset:2048
	ds_read_b128 v[170:173], v144 offset:3072
	s_mov_b64 s[46:47], s[40:41]
	s_add_i32 m0, s91, 0xc000
	ds_read_b128 v[174:177], v149
	ds_read_b128 v[180:183], v149 offset:1024
	ds_read_b128 v[184:187], v149 offset:2048
	ds_read_b128 v[188:191], v149 offset:3072
	ds_read_b128 v[192:195], v149 offset:4096
	ds_read_b128 v[196:199], v149 offset:5120
	ds_read_b128 v[200:203], v149 offset:6144
	ds_read_b128 v[210:213], v149 offset:7168
	s_cmp_eq_u32 s76, s101
	s_cbranch_scc1 .Lgin_skipw0
	global_load_lds_dwordx4 v134, s[46:47]
	s_add_i32 m0, s91, 0xe000
	s_nop 0
	s_add_u32 s36, s46, 0x40000
	s_addc_u32 s37, s47, 0
	global_load_lds_dwordx4 v134, s[36:37]
	s_waitcnt vmcnt(8)

; #define PG8_SB(B) __builtin_amdgcn_rcpf(1.f + expneg(B))
; #define PG8_SB(B) __builtin_amdgcn_rcpf(1.f + expneg(B))
; #define PG8_STAGE(bufoff, gbase, voff) do { _Pragma("unroll") for (int _i = 0; _i < 2; ++_i) \
;         __builtin_amdgcn_global_load_lds((const unsigned*)((const char*)(gbase) + (size_t)_i * qstep + (voff)[0]), (PG8_LAS unsigned*)(lds + (bufoff) + ldsw + _i * 8192), 16, 0, 0); } while (0)
; #define PG8_LDA(dst, b, h) do { _Pragma("unroll") for (int m = 0; m < 4; ++m) _Pragma("unroll") for (int k = 0; k < 2; ++k) dst[m][k] = *(const PG8_LAS bf16x8*)(lds + PG8_SA(b, h) + aoff + m * 2048 + k * 1024); } while (0)
; #define PG8_LDB(dst, b, h) do { _Pragma("unroll") for (int n = 0; n < 2; ++n) _Pragma("unroll") for (int k = 0; k < 2; ++k) dst[n][k] = *(const PG8_LAS bf16x8*)(lds + PG8_SB(b, h) + boff + n * 2048 + k * 1024); } while (0)
; #define PG8_MMA(ai, bj, At, Bt) do { __builtin_amdgcn_s_setprio(1); _Pragma("unroll") for (int m = 0; m < 4; ++m) _Pragma("unroll") for (int n = 0; n < 2; ++n) _Pragma("unroll") for (int k = 0; k < 2; ++k) \
;         acc[ai][bj][m][n] = __builtin_amdgcn_mfma_f32_16x16x32_bf16(Bt[n][k], At[m][k], acc[ai][bj][m][n], 0, 0, 0); __builtin_amdgcn_s_setprio(0); } while (0)
; #define PG8_WAIT_V89() do { if constexpr (SLIVER) PG8_WAIT_V(9); else PG8_WAIT_V(8); } while (0)
; #define PG8_WAIT_L(n) asm volatile("s_waitcnt lgkmcnt(" #n ")" ::: "memory")
; #define PG8_BAR __builtin_amdgcn_s_barrier()
; template <class Epi, class Sched, bool ALIGN_EPI = false, bool SP2 = false, bool SLIVER = false>
; __device__ __forceinline__ void gemm_phase(PG8_LAS unsigned char* lds, const Gemm g, const Sched& S, const Epi& E) {
;     ...
;             PG8_WAIT_V89(); PG8_WAIT_L(0); PG8_BAR; PG8_MMA(0, 0, At, B0); PG8_MMA(0, 1, At, B1); PG8_BAR; PG8_SCHED;
;             PG8_LDA(At, 0, 1); PG8_LDS_S(0); PG8_STAGE(PG8_SB(0, 0), b2, voffB); PG8_STAGE(PG8_SB(0, 1), b2 + hstep, voffB); PG8_STAGE(PG8_SA(0, 0), a2, voffA);
;             PG8_WAIT_V89(); PG8_WAIT_L(0); PG8_BAR; PG8_MMA(1, 0, At, B0); PG8_MMA(1, 1, At, B1); PG8_MMA_S(); PG8_BAR; PG8_SCHED;
;             PG8_LDB(B0, 1, 0); PG8_LDB(B1, 1, 1); PG8_SCHED; PG8_LDA(At, 1, 0); PG8_STAGE(PG8_SA(0, 1), a2 + hstep, voffA); PG8_STAGE_S(0, s2);
;             PG8_WAIT_V89(); PG8_WAIT_L(0); PG8_BAR; PG8_MMA(0, 0, At, B0); PG8_MMA(0, 1, At, B1); PG8_BAR; PG8_SCHED;
.Lgin_skipw1:
	s_waitcnt lgkmcnt(0)
	s_setprio 1
	s_barrier
	v_mfma_f32_16x16x32_bf16 v[62:65], v[136:139], v[174:177], v[62:65]
	v_mfma_f32_16x16x32_bf16 v[58:61], v[150:153], v[174:177], v[58:61]
	v_mfma_f32_16x16x32_bf16 v[50:53], v[136:139], v[184:187], v[50:53]
	v_mfma_f32_16x16x32_bf16 v[42:45], v[150:153], v[184:187], v[42:45]
	v_mfma_f32_16x16x32_bf16 v[34:37], v[136:139], v[192:195], v[34:37]
	v_mfma_f32_16x16x32_bf16 v[26:29], v[150:153], v[192:195], v[26:29]
	v_mfma_f32_16x16x32_bf16 v[18:21], v[136:139], v[200:203], v[18:21]
	v_mfma_f32_16x16x32_bf16 v[10:13], v[150:153], v[200:203], v[10:13]
	v_mfma_f32_16x16x32_bf16 v[62:65], v[140:143], v[180:183], v[62:65]
	v_mfma_f32_16x16x32_bf16 v[58:61], v[154:157], v[180:183], v[58:61]
	v_mfma_f32_16x16x32_bf16 v[50:53], v[140:143], v[188:191], v[50:53]
	v_mfma_f32_16x16x32_bf16 v[42:45], v[154:157], v[188:191], v[42:45]
	v_mfma_f32_16x16x32_bf16 v[34:37], v[140:143], v[196:199], v[34:37]
	v_mfma_f32_16x16x32_bf16 v[26:29], v[154:157], v[196:199], v[26:29]
	v_mfma_f32_16x16x32_bf16 v[18:21], v[140:143], v[210:213], v[18:21]
	v_mfma_f32_16x16x32_bf16 v[10:13], v[154:157], v[210:213], v[10:13]
	s_setprio 0
	s_setprio 1
	v_mfma_f32_16x16x32_bf16 v[54:57], v[158:161], v[174:177], v[54:57]
	v_mfma_f32_16x16x32_bf16 v[46:49], v[166:169], v[174:177], v[46:49]
	v_mfma_f32_16x16x32_bf16 v[38:41], v[158:161], v[184:187], v[38:41]
	v_mfma_f32_16x16x32_bf16 v[30:33], v[166:169], v[184:187], v[30:33]
	v_mfma_f32_16x16x32_bf16 v[22:25], v[158:161], v[192:195], v[22:25]
	v_mfma_f32_16x16x32_bf16 v[14:17], v[166:169], v[192:195], v[14:17]
	v_mfma_f32_16x16x32_bf16 v[6:9], v[158:161], v[200:203], v[6:9]
	v_mfma_f32_16x16x32_bf16 v[2:5], v[166:169], v[200:203], v[2:5]
	v_mfma_f32_16x16x32_bf16 v[54:57], v[162:165], v[180:183], v[54:57]
	v_mfma_f32_16x16x32_bf16 v[46:49], v[170:173], v[180:183], v[46:49]
	v_mfma_f32_16x16x32_bf16 v[38:41], v[162:165], v[188:191], v[38:41]
	v_mfma_f32_16x16x32_bf16 v[30:33], v[170:173], v[188:191], v[30:33]
	v_mfma_f32_16x16x32_bf16 v[22:25], v[162:165], v[196:199], v[22:25]
	v_mfma_f32_16x16x32_bf16 v[14:17], v[170:173], v[196:199], v[14:17]
	v_mfma_f32_16x16x32_bf16 v[6:9], v[162:165], v[210:213], v[6:9]
	v_mfma_f32_16x16x32_bf16 v[2:5], v[170:173], v[210:213], v[2:5]
	s_barrier
	s_setprio 0
	s_add_i32 s62, 0, 0x18000
	v_add_u32_e32 v144, s62, v145
	s_add_i32 s63, 0, 0x1c000
	ds_read_b128 v[136:139], v144
	ds_read_b128 v[140:143], v144 offset:1024
	ds_read_b128 v[150:153], v144 offset:2048
	ds_read_b128 v[154:157], v144 offset:3072
	v_add_u32_e32 v144, s63, v145
	ds_read_b128 v[158:161], v144
	ds_read_b128 v[162:165], v144 offset:1024
	ds_read_b128 v[166:169], v144 offset:2048
	ds_read_b128 v[170:173], v144 offset:3072
	s_mov_b32 m0, s51
	ds_read_b128 v[174:177], v149 offset:32768
	ds_read_b128 v[180:183], v149 offset:33792
	ds_read_b128 v[184:187], v149 offset:34816
	ds_read_b128 v[188:191], v149 offset:35840
	ds_read_b128 v[192:195], v149 offset:36864
	ds_read_b128 v[196:199], v149 offset:37888
	ds_read_b128 v[200:203], v149 offset:38912
	ds_read_b128 v[210:213], v149 offset:39936
	s_add_u32 s60, s46, 0x80000
	s_addc_u32 s61, s47, 0
	global_load_lds_dwordx4 v130, s[60:61]
	s_mov_b32 m0, s54
	s_nop 0
	s_add_u32 s36, s46, 0xc0000
	s_addc_u32 s37, s47, 0
	global_load_lds_dwordx4 v130, s[36:37]
	s_cmp_eq_u32 s76, s101
	s_cbranch_scc1 .Lgin_skipw2
	s_waitcnt vmcnt(8)
.Lgin_skipw2:
	s_waitcnt lgkmcnt(0)
	s_setprio 1
	s_barrier
	v_mfma_f32_16x16x32_bf16 v[126:129], v[136:139], v[174:177], v[126:129]
	v_mfma_f32_16x16x32_bf16 v[122:125], v[150:153], v[174:177], v[122:125]
	v_mfma_f32_16x16x32_bf16 v[114:117], v[136:139], v[184:187], v[114:117]
	v_mfma_f32_16x16x32_bf16 v[106:109], v[150:153], v[184:187], v[106:109]
	v_mfma_f32_16x16x32_bf16 v[98:101], v[136:139], v[192:195], v[98:101]
	v_mfma_f32_16x16x32_bf16 v[90:93], v[150:153], v[192:195], v[90:93]
	v_mfma_f32_16x16x32_bf16 v[82:85], v[136:139], v[200:203], v[82:85]
	v_mfma_f32_16x16x32_bf16 v[74:77], v[150:153], v[200:203], v[74:77]
	v_mfma_f32_16x16x32_bf16 v[126:129], v[140:143], v[180:183], v[126:129]
	v_mfma_f32_16x16x32_bf16 v[122:125], v[154:157], v[180:183], v[122:125]
	v_mfma_f32_16x16x32_bf16 v[114:117], v[140:143], v[188:191], v[114:117]
	v_mfma_f32_16x16x32_bf16 v[106:109], v[154:157], v[188:191], v[106:109]
	v_mfma_f32_16x16x32_bf16 v[98:101], v[140:143], v[196:199], v[98:101]
	v_mfma_f32_16x16x32_bf16 v[90:93], v[154:157], v[196:199], v[90:93]
	v_mfma_f32_16x16x32_bf16 v[82:85], v[140:143], v[210:213], v[82:85]
	v_mfma_f32_16x16x32_bf16 v[74:77], v[154:157], v[210:213], v[74:77]
	s_setprio 0
	s_setprio 1
	v_mfma_f32_16x16x32_bf16 v[118:121], v[158:161], v[174:177], v[118:121]
	v_mfma_f32_16x16x32_bf16 v[110:113], v[166:169], v[174:177], v[110:113]
	v_mfma_f32_16x16x32_bf16 v[102:105], v[158:161], v[184:187], v[102:105]
	v_mfma_f32_16x16x32_bf16 v[94:97], v[166:169], v[184:187], v[94:97]
	v_mfma_f32_16x16x32_bf16 v[86:89], v[158:161], v[192:195], v[86:89]
	v_mfma_f32_16x16x32_bf16 v[78:81], v[166:169], v[192:195], v[78:81]
	v_mfma_f32_16x16x32_bf16 v[70:73], v[158:161], v[200:203], v[70:73]
	v_mfma_f32_16x16x32_bf16 v[66:69], v[166:169], v[200:203], v[66:69]
	v_mfma_f32_16x16x32_bf16 v[118:121], v[162:165], v[180:183], v[118:121]
	v_mfma_f32_16x16x32_bf16 v[110:113], v[170:173], v[180:183], v[110:113]
	v_mfma_f32_16x16x32_bf16 v[102:105], v[162:165], v[188:191], v[102:105]
	v_mfma_f32_16x16x32_bf16 v[94:97], v[170:173], v[188:191], v[94:97]
	v_mfma_f32_16x16x32_bf16 v[86:89], v[162:165], v[196:199], v[86:89]
	v_mfma_f32_16x16x32_bf16 v[78:81], v[170:173], v[196:199], v[78:81]
	v_mfma_f32_16x16x32_bf16 v[70:73], v[162:165], v[210:213], v[70:73]
	v_mfma_f32_16x16x32_bf16 v[66:69], v[170:173], v[210:213], v[66:69]
	s_barrier
; #define PG8_SB(B) __builtin_amdgcn_rcpf(1.f + expneg(B))
; #define PG8_SB(B) __builtin_amdgcn_rcpf(1.f + expneg(B))
; #define PG8_STAGE(bufoff, gbase, voff) do { _Pragma("unroll") for (int _i = 0; _i < 2; ++_i) \
;         __builtin_amdgcn_global_load_lds((const unsigned*)((const char*)(gbase) + (size_t)_i * qstep + (voff)[0]), (PG8_LAS unsigned*)(lds + (bufoff) + ldsw + _i * 8192), 16, 0, 0); } while (0)
; #define PG8_LDA(dst, b, h) do { _Pragma("unroll") for (int m = 0; m < 4; ++m) _Pragma("unroll") for (int k = 0; k < 2; ++k) dst[m][k] = *(const PG8_LAS bf16x8*)(lds + PG8_SA(b, h) + aoff + m * 2048 + k * 1024); } while (0)
; #define PG8_WAIT_V89() do { if constexpr (SLIVER) PG8_WAIT_V(9); else PG8_WAIT_V(8); } while (0)
; #define PG8_WAIT_L(n) asm volatile("s_waitcnt lgkmcnt(" #n ")" ::: "memory")
; #define PG8_BAR __builtin_amdgcn_s_barrier()
;     __device__ __forceinline__ void operator()(const f32x4 (&acc)[2][2][4][2], const Unit& u, int wr, int wc, int fr, int fq) const {
;         const int pn = u.pn, rowt = u.pm * BM + wr * 64 + fr, colw = wc * 32 + 8 * fq;
;         float rsv[2][4];
; #pragma unroll
;         for (int ai = 0; ai < 2; ++ai)
; #pragma unroll
;             for (int m = 0; m < 4; ++m) rsv[ai][m] = row_rstd(ss, rowt + ai * HALF + m * 16);
; template <class Epi, class Sched, bool ALIGN_EPI = false, bool SP2 = false, bool SLIVER = false>
; __device__ __forceinline__ void gemm_phase(PG8_LAS unsigned char* lds, const Gemm g, const Sched& S, const Epi& E) {
;     ...
;             PG8_LDA(At, 1, 1); PG8_LDS_S(1); PG8_STAGE(PG8_SB(1, 0), b3, voffB); PG8_STAGE(PG8_SB(1, 1), b3 + hstep, voffB); PG8_STAGE(PG8_SA(1, 0), a3, voffA);
;             PG8_WAIT_V89(); PG8_WAIT_L(0); PG8_BAR; PG8_MMA(1, 0, At, B0); PG8_MMA(1, 1, At, B1); PG8_MMA_S(); PG8_BAR; PG8_SCHED;
;     ...
;         if constexpr (ALIGN_EPI) { if (wr == 0) PG8_BAR; }
;         const bool fin = Epi::final_seg(cur.seg);
;         if constexpr (!Epi::AFTER_DRAIN) { int l2_ = threadIdx.x; asm volatile("" : "+v"(l2_)); const int fr2 = l2_ & 15, fq2 = (l2_ >> 4) & 3;
;             if (fin) { E(acc, cur, wr, wc, fr2, fq2); if constexpr (SLIVER) E.sliver(accs, cur, S.srow0, wr, wc, fr2, fq2); E.finish(cur, S.srow0, l2_); } else { E.mid(acc, cur, wr, wc, fr2, fq2); if constexpr (SLIVER) E.sliver_mid(accs, cur, S.srow0, wr, wc, fr2, fq2); } S.done(cur); }
	s_setprio 0
	s_add_i32 s62, s62, s53
	s_mov_b32 m0, s62
	ds_read_b128 v[174:177], v149 offset:49152
	ds_read_b128 v[180:183], v149 offset:50176
	ds_read_b128 v[184:187], v149 offset:51200
	ds_read_b128 v[188:191], v149 offset:52224
	ds_read_b128 v[192:195], v149 offset:53248
	ds_read_b128 v[196:199], v149 offset:54272
	ds_read_b128 v[200:203], v149 offset:55296
	ds_read_b128 v[210:213], v149 offset:56320
	s_add_u32 s58, s78, 0x80
	s_addc_u32 s59, s79, 0
	global_load_lds_dwordx4 v132, s[58:59]
	s_add_i32 m0, s62, 0x2000
	s_add_i32 s62, s63, s53
	s_add_u32 s60, s78, 0x40080
	s_addc_u32 s61, s79, 0
	global_load_lds_dwordx4 v132, s[60:61]
	s_mov_b32 m0, s62
	s_add_u32 s36, s78, 0x80080
	s_addc_u32 s37, s79, 0
	global_load_lds_dwordx4 v132, s[36:37]
	s_add_i32 m0, s62, 0x2000
	s_nop 0
	s_add_u32 s58, s78, 0xc0080
	s_addc_u32 s59, s79, 0
	global_load_lds_dwordx4 v132, s[58:59]
	s_mov_b32 m0, s10
	s_nop 0
	s_add_u32 s60, s46, 0x80
	s_addc_u32 s61, s47, 0
	global_load_lds_dwordx4 v130, s[60:61]
	s_mov_b32 m0, s55
	s_nop 0
	s_add_u32 s36, s46, 0x40080
	s_addc_u32 s37, s47, 0
	global_load_lds_dwordx4 v130, s[36:37]
	s_waitcnt vmcnt(8)
	s_waitcnt lgkmcnt(0)
	s_setprio 1
	s_barrier
	v_mfma_f32_16x16x32_bf16 v[62:65], v[136:139], v[174:177], v[62:65]
	v_mfma_f32_16x16x32_bf16 v[58:61], v[150:153], v[174:177], v[58:61]
	v_mfma_f32_16x16x32_bf16 v[50:53], v[136:139], v[184:187], v[50:53]
	v_mfma_f32_16x16x32_bf16 v[42:45], v[150:153], v[184:187], v[42:45]
	v_mfma_f32_16x16x32_bf16 v[34:37], v[136:139], v[192:195], v[34:37]
	v_mfma_f32_16x16x32_bf16 v[26:29], v[150:153], v[192:195], v[26:29]
	v_mfma_f32_16x16x32_bf16 v[18:21], v[136:139], v[200:203], v[18:21]
	v_mfma_f32_16x16x32_bf16 v[10:13], v[150:153], v[200:203], v[10:13]
	v_mfma_f32_16x16x32_bf16 v[62:65], v[140:143], v[180:183], v[62:65]
	v_mfma_f32_16x16x32_bf16 v[58:61], v[154:157], v[180:183], v[58:61]
	v_mfma_f32_16x16x32_bf16 v[50:53], v[140:143], v[188:191], v[50:53]
	v_mfma_f32_16x16x32_bf16 v[42:45], v[154:157], v[188:191], v[42:45]
	v_mfma_f32_16x16x32_bf16 v[34:37], v[140:143], v[196:199], v[34:37]
	v_mfma_f32_16x16x32_bf16 v[26:29], v[154:157], v[196:199], v[26:29]
	v_mfma_f32_16x16x32_bf16 v[18:21], v[140:143], v[210:213], v[18:21]
	v_mfma_f32_16x16x32_bf16 v[10:13], v[154:157], v[210:213], v[10:13]
	s_setprio 0
	s_setprio 1
	v_mfma_f32_16x16x32_bf16 v[54:57], v[158:161], v[174:177], v[54:57]
	v_mfma_f32_16x16x32_bf16 v[46:49], v[166:169], v[174:177], v[46:49]
	v_mfma_f32_16x16x32_bf16 v[38:41], v[158:161], v[184:187], v[38:41]
	v_mfma_f32_16x16x32_bf16 v[30:33], v[166:169], v[184:187], v[30:33]
	v_mfma_f32_16x16x32_bf16 v[22:25], v[158:161], v[192:195], v[22:25]
	v_mfma_f32_16x16x32_bf16 v[14:17], v[166:169], v[192:195], v[14:17]
	v_mfma_f32_16x16x32_bf16 v[6:9], v[158:161], v[200:203], v[6:9]
	v_mfma_f32_16x16x32_bf16 v[2:5], v[166:169], v[200:203], v[2:5]
	v_mfma_f32_16x16x32_bf16 v[54:57], v[162:165], v[180:183], v[54:57]
	v_mfma_f32_16x16x32_bf16 v[46:49], v[170:173], v[180:183], v[46:49]
	v_mfma_f32_16x16x32_bf16 v[38:41], v[162:165], v[188:191], v[38:41]
	v_mfma_f32_16x16x32_bf16 v[30:33], v[170:173], v[188:191], v[30:33]
	v_mfma_f32_16x16x32_bf16 v[22:25], v[162:165], v[196:199], v[22:25]
	v_mfma_f32_16x16x32_bf16 v[14:17], v[170:173], v[196:199], v[14:17]
	v_mfma_f32_16x16x32_bf16 v[6:9], v[162:165], v[210:213], v[6:9]
	v_mfma_f32_16x16x32_bf16 v[2:5], v[170:173], v[210:213], v[2:5]
	s_barrier
	s_setprio 0
	s_add_i32 s76, s76, 2
	s_add_u32 s40, s40, 0x100
	s_addc_u32 s41, s41, 0
	s_add_u32 s68, s68, 0x100
	s_addc_u32 s69, s69, 0
	s_cmp_gt_u32 s76, 29
	s_cbranch_scc0 .LBB0_153
	s_and_b64 vcc, exec, s[48:49]
	s_cbranch_vccz .LBB0_156
	s_barrier
.LBB0_156:
	s_add_u32 s36, s13, 0x80080
	s_addc_u32 s37, s12, 0
	s_add_i32 m0, s91, 0xc000
	s_nop 0
	global_load_lds_dwordx4 v134, s[36:37]
	s_add_u32 s36, s36, 0x40000
	s_addc_u32 s37, s37, 0
	s_add_i32 m0, s91, 0xe000
	s_nop 0
	global_load_lds_dwordx4 v134, s[36:37]
	v_mov_b32_e32 v138, v0
	s_lshl_b32 s12, s92, 8
	s_add_i32 s12, s12, s16
	v_and_b32_e32 v159, 15, v138
	v_or_b32_e32 v156, s12, v159
	v_ashrrev_i32_e32 v157, 31, v156
	v_or_b32_e32 v154, 16, v156
	v_lshl_add_u64 v[136:137], v[156:157], 4, s[18:19]
	v_ashrrev_i32_e32 v155, 31, v154
	v_or_b32_e32 v150, 32, v156
	v_mov_b32_e32 v160, v214
	v_mov_b32_e32 v161, v215
	v_mov_b32_e32 v162, v216
	v_mov_b32_e32 v163, v217
	v_lshl_add_u64 v[136:137], v[154:155], 4, s[18:19]
	v_ashrrev_i32_e32 v151, 31, v150
	v_mov_b32_e32 v164, v218
	v_mov_b32_e32 v165, v219
	v_mov_b32_e32 v166, v220
	v_mov_b32_e32 v167, v221
	v_lshl_add_u64 v[136:137], v[150:151], 4, s[18:19]
	v_mov_b32_e32 v168, v222
	v_mov_b32_e32 v169, v223
	v_mov_b32_e32 v170, v224
	v_mov_b32_e32 v171, v225
	v_or_b32_e32 v146, 48, v156
	v_ashrrev_i32_e32 v147, 31, v146
	v_lshl_add_u64 v[136:137], v[146:147], 4, s[18:19]
	v_mov_b32_e32 v172, v226
	v_mov_b32_e32 v173, v227
	v_mov_b32_e32 v174, v228
	v_mov_b32_e32 v175, v229
	v_add_u32_e32 v142, 0x80, v156
	v_ashrrev_i32_e32 v143, 31, v142
	v_lshl_add_u64 v[136:137], v[142:143], 4, s[18:19]
	v_mov_b32_e32 v180, v230
	v_mov_b32_e32 v181, v231
	v_mov_b32_e32 v182, v232
	v_mov_b32_e32 v183, v233
	v_add_u32_e32 v140, 0x90, v156
	v_add_u32_e32 v136, 0xb0, v156
	v_lshrrev_b32_e32 v178, 1, v138
	v_add_u32_e32 v138, 0xa0, v156
	v_ashrrev_i32_e32 v141, 31, v140
	v_ashrrev_i32_e32 v137, 31, v136
	v_ashrrev_i32_e32 v139, 31, v138
	v_lshl_add_u64 v[152:153], v[140:141], 4, s[18:19]
	v_lshl_add_u64 v[192:193], v[136:137], 4, s[18:19]
	v_lshl_add_u64 v[176:177], v[138:139], 4, s[18:19]
	v_mov_b32_e32 v184, v240
	v_mov_b32_e32 v185, v241
	v_mov_b32_e32 v186, v242
	v_mov_b32_e32 v187, v243
	v_mov_b32_e32 v188, v244
	v_mov_b32_e32 v189, v245
	v_mov_b32_e32 v190, v246
	v_mov_b32_e32 v191, v247
	s_nop 0
	v_mov_b32_e32 v192, v248
	v_mov_b32_e32 v193, v249
	v_mov_b32_e32 v194, v250
	v_mov_b32_e32 v195, v251
	s_sub_i32 s12, s90, 36
	s_cmp_gt_u32 s12, 0xffffffef
	s_mov_b64 s[12:13], -1
	v_readlane_b32 s79, v254, 35
	s_movk_i32 s77, 0x70
	s_mov_b64 s[68:69], 0x4000c00
	s_waitcnt vmcnt(0)
; __device__ __forceinline__ u32x4 pack8(const f32x4& a, const f32x4& b) { u32x4 w; w.x = cvt_pk_bf16(a[0], a[1]); w.y = cvt_pk_bf16(a[2], a[3]); w.z = cvt_pk_bf16(b[0], b[1]); w.w = cvt_pk_bf16(b[2], b[3]); return w; }
; __device__ __forceinline__ float ss_total(const u32x4 a) { return ((bflo(a.x) + bfhi(a.x)) + (bflo(a.y) + bfhi(a.y))) + ((bflo(a.z) + bfhi(a.z)) + (bflo(a.w) + bfhi(a.w))); }
; __device__ __forceinline__ float row_rstd(const bf16_t* ss, int row) { const u32x4 a = *(const u32x4*)(ss + (size_t)row * 8);
;     return __builtin_amdgcn_rsqf(ss_total(a) * (1.f / 2048.f) + 1e-6f); }
;     __device__ __forceinline__ void operator()(const f32x4 (&acc)[2][2][4][2], const Unit& u, int wr, int wc, int fr, int fq) const {
;         const int pn = u.pn, rowt = u.pm * BM + wr * 64 + fr, colw = wc * 32 + 8 * fq;
;         float rsv[2][4];
; #pragma unroll
;         for (int ai = 0; ai < 2; ++ai)
; #pragma unroll
;             for (int m = 0; m < 4; ++m) rsv[ai][m] = row_rstd(ss, rowt + ai * HALF + m * 16);
;         if (pn < 20 || pn >= 36) {
;             bf16_t* base; int ld, colt;
;             if (pn < 12) { base = (bf16_t*)(ws + WS_ZC); ld = 3072; colt = pn * 256; }
;             else if (pn < 20) { base = (bf16_t*)(ws + WS_QB); ld = 2048; colt = (pn - 12) * 256; }
;             else { base = (bf16_t*)(ws + WS_GG); ld = 4096; colt = (pn - 36) * 256; }
; #pragma unroll
;             for (int ai = 0; ai < 2; ++ai)
; #pragma unroll
;                 for (int m = 0; m < 4; ++m) { const int row = rowt + ai * HALF + m * 16; bf16_t* rowp = base + (size_t)row * ld + colt + colw; const float rs = rsv[ai][m];
; #pragma unroll
;                     for (int bj = 0; bj < 2; ++bj) *(u32x4*)(rowp + bj * HALF) = pack8(acc[ai][bj][m][0] * rs, acc[ai][bj][m][1] * rs); }
;         } else {
;             const bool isv = pn >= 28; const int colt = (pn - (isv ? 28 : 20)) * 256 + colw;
;             float* fbase; bf16_t* bbase;
;             if (u.pm < 32) { fbase = out + (isv ? O_VP : O_KP) + (size_t)L * MP * DM; bbase = (bf16_t*)(ws + (isv ? WS_VB : WS_KB)); }
;             else { fbase = out + (isv ? O_VS : O_KS) + (size_t)L * MS * DM; bbase = (bf16_t*)(ws + (isv ? WS_VALL : WS_KALL)) + (size_t)L * DB * KROWS * DM; }
	v_lshlrev_b32_e32 v144, 16, v160
	v_and_b32_e32 v148, 0xffff0000, v160
	v_lshlrev_b32_e32 v152, 16, v161
	v_and_b32_e32 v153, 0xffff0000, v161
	v_lshlrev_b32_e32 v158, 16, v162
	v_and_b32_e32 v160, 0xffff0000, v162
	v_lshlrev_b32_e32 v161, 16, v163
	v_and_b32_e32 v162, 0xffff0000, v163
	v_add_f32_e32 v144, v144, v148
	v_add_f32_e32 v148, v152, v153
	v_add_f32_e32 v152, v158, v160
	v_add_f32_e32 v153, v161, v162
	v_lshlrev_b32_e32 v158, 16, v164
	v_and_b32_e32 v160, 0xffff0000, v164
	v_lshlrev_b32_e32 v161, 16, v165
	v_and_b32_e32 v162, 0xffff0000, v165
	v_lshlrev_b32_e32 v163, 16, v166
	v_and_b32_e32 v164, 0xffff0000, v166
	v_lshlrev_b32_e32 v165, 16, v167
	v_and_b32_e32 v166, 0xffff0000, v167
	v_lshlrev_b32_e32 v167, 16, v168
	v_and_b32_e32 v168, 0xffff0000, v168
	v_lshlrev_b32_e32 v176, 16, v169
	v_and_b32_e32 v169, 0xffff0000, v169
	v_lshlrev_b32_e32 v177, 16, v170
	v_and_b32_e32 v170, 0xffff0000, v170
	v_lshlrev_b32_e32 v196, 16, v171
	v_and_b32_e32 v171, 0xffff0000, v171
	v_add_f32_e32 v144, v144, v148
	v_add_f32_e32 v148, v152, v153
	v_add_f32_e32 v152, v158, v160
	v_add_f32_e32 v153, v161, v162
	v_add_f32_e32 v158, v163, v164
	v_add_f32_e32 v160, v165, v166
	v_add_f32_e32 v161, v167, v168
	v_add_f32_e32 v162, v176, v169
	v_add_f32_e32 v163, v177, v170
	v_add_f32_e32 v164, v196, v171
	v_add_f32_e32 v144, v144, v148
	v_add_f32_e32 v148, v152, v153
	v_add_f32_e32 v152, v158, v160
	v_add_f32_e32 v153, v161, v162
	v_add_f32_e32 v158, v163, v164
	v_fmamk_f32 v144, v144, 0x3a000000, v1
	v_add_f32_e32 v148, v148, v152
	v_add_f32_e32 v152, v153, v158
	v_rsq_f32_e32 v166, v144
	v_fmamk_f32 v144, v148, 0x3a000000, v1
	v_fmamk_f32 v148, v152, 0x3a000000, v1
	v_rsq_f32_e32 v162, v148
	v_lshlrev_b32_e32 v148, 16, v174
	v_and_b32_e32 v152, 0xffff0000, v174
	v_lshlrev_b32_e32 v197, 16, v172
	v_and_b32_e32 v172, 0xffff0000, v172
	v_lshlrev_b32_e32 v198, 16, v173
	v_rsq_f32_e32 v164, v144
	v_and_b32_e32 v144, 0xffff0000, v173
	v_add_f32_e32 v148, v148, v152
	v_lshlrev_b32_e32 v152, 16, v175
	v_and_b32_e32 v153, 0xffff0000, v175
	v_add_f32_e32 v165, v197, v172
	v_add_f32_e32 v144, v198, v144
	v_add_f32_e32 v152, v152, v153
	v_add_f32_e32 v144, v165, v144
	v_add_f32_e32 v148, v148, v152
	v_add_f32_e32 v144, v144, v148
	v_fmamk_f32 v144, v144, 0x3a000000, v1
	v_rsq_f32_e32 v160, v144
	v_lshlrev_b32_e32 v144, 16, v180
	v_and_b32_e32 v148, 0xffff0000, v180
	v_add_f32_e32 v144, v144, v148
	v_lshlrev_b32_e32 v148, 16, v181
	v_and_b32_e32 v152, 0xffff0000, v181
	v_add_f32_e32 v148, v148, v152
	v_add_f32_e32 v144, v144, v148
	v_lshlrev_b32_e32 v148, 16, v182
	v_and_b32_e32 v152, 0xffff0000, v182
	v_add_f32_e32 v148, v148, v152
	v_lshlrev_b32_e32 v152, 16, v183
	v_and_b32_e32 v153, 0xffff0000, v183
	v_add_f32_e32 v152, v152, v153
	v_add_f32_e32 v148, v148, v152
	v_add_f32_e32 v144, v144, v148
	v_fmamk_f32 v144, v144, 0x3a000000, v1
	v_rsq_f32_e32 v158, v144
	v_lshlrev_b32_e32 v144, 16, v184
	v_and_b32_e32 v148, 0xffff0000, v184
	v_add_f32_e32 v144, v144, v148
	v_lshlrev_b32_e32 v148, 16, v185
	v_and_b32_e32 v152, 0xffff0000, v185
	v_add_f32_e32 v148, v148, v152
	v_add_f32_e32 v144, v144, v148
	v_lshlrev_b32_e32 v148, 16, v186
	v_and_b32_e32 v152, 0xffff0000, v186
	v_add_f32_e32 v148, v148, v152
	v_lshlrev_b32_e32 v152, 16, v187
	v_and_b32_e32 v153, 0xffff0000, v187
	v_add_f32_e32 v152, v152, v153
	v_add_f32_e32 v148, v148, v152
	v_add_f32_e32 v144, v144, v148
	v_fmamk_f32 v144, v144, 0x3a000000, v1
	v_rsq_f32_e32 v152, v144
	v_lshlrev_b32_e32 v144, 16, v188
	v_and_b32_e32 v148, 0xffff0000, v188
	v_add_f32_e32 v144, v144, v148
	v_lshlrev_b32_e32 v148, 16, v189
	v_and_b32_e32 v153, 0xffff0000, v189
	v_add_f32_e32 v148, v148, v153
	v_add_f32_e32 v144, v144, v148
	v_lshlrev_b32_e32 v148, 16, v190
	v_and_b32_e32 v153, 0xffff0000, v190
	v_add_f32_e32 v148, v148, v153
	v_lshlrev_b32_e32 v153, 16, v191
	v_and_b32_e32 v161, 0xffff0000, v191
	v_add_f32_e32 v153, v153, v161
	v_add_f32_e32 v148, v148, v153
	v_add_f32_e32 v144, v144, v148
	v_fmamk_f32 v144, v144, 0x3a000000, v1
	v_rsq_f32_e32 v148, v144
	v_lshlrev_b32_e32 v144, 16, v192
	v_and_b32_e32 v153, 0xffff0000, v192
	v_add_f32_e32 v144, v144, v153
	v_lshlrev_b32_e32 v153, 16, v193
	v_and_b32_e32 v161, 0xffff0000, v193
	v_add_f32_e32 v153, v153, v161
	v_add_f32_e32 v144, v144, v153
	v_lshlrev_b32_e32 v153, 16, v194
	v_and_b32_e32 v161, 0xffff0000, v194
	v_add_f32_e32 v153, v153, v161
	v_lshlrev_b32_e32 v161, 16, v195
	v_and_b32_e32 v163, 0xffff0000, v195
	v_add_f32_e32 v161, v161, v163
	v_add_f32_e32 v153, v153, v161
	v_add_f32_e32 v144, v144, v153
	v_fmamk_f32 v144, v144, 0x3a000000, v1
	v_rsq_f32_e32 v144, v144
	v_and_or_b32 v153, v178, 24, s17
	s_cbranch_scc0 .LBB0_195
	s_cmp_gt_u32 s90, 27
	s_cselect_b64 s[40:41], -1, 0
	s_cmp_gt_i32 s92, 31
	s_cselect_b64 s[92:93], -1, 0
	s_mov_b64 s[94:95], -1
	s_and_b64 vcc, exec, s[92:93]
	s_cbranch_vccz .LBB0_159
	s_and_b64 s[12:13], s[40:41], exec
	s_mov_b32 s12, 0x25420000
	s_cselect_b32 s12, s12, 0x24420000
	v_readlane_b32 s13, v254, 50
	s_add_u32 s62, s13, s12
	v_readlane_b32 s12, v254, 53
	s_addc_u32 s63, s12, 0
	s_and_b64 s[12:13], s[40:41], exec
	s_mov_b32 s12, 0x2dd00000
	s_cselect_b32 s12, s12, 0x24d00000
	v_readlane_b32 s13, v254, 47
	s_add_u32 s80, s13, s12
	v_readlane_b32 s12, v254, 48
	s_addc_u32 s81, s12, 0
	s_mov_b64 s[94:95], 0

; #define PG8_STAGE(bufoff, gbase, voff) do { _Pragma("unroll") for (int _i = 0; _i < 2; ++_i) \
;         __builtin_amdgcn_global_load_lds((const unsigned*)((const char*)(gbase) + (size_t)_i * qstep + (voff)[0]), (PG8_LAS unsigned*)(lds + (bufoff) + ldsw + _i * 8192), 16, 0, 0); } while (0)
; #define PG8_LDA(dst, b, h) do { _Pragma("unroll") for (int m = 0; m < 4; ++m) _Pragma("unroll") for (int k = 0; k < 2; ++k) dst[m][k] = *(const PG8_LAS bf16x8*)(lds + PG8_SA(b, h) + aoff + m * 2048 + k * 1024); } while (0)
; #define PG8_LDB(dst, b, h) do { _Pragma("unroll") for (int n = 0; n < 2; ++n) _Pragma("unroll") for (int k = 0; k < 2; ++k) dst[n][k] = *(const PG8_LAS bf16x8*)(lds + PG8_SB(b, h) + boff + n * 2048 + k * 1024); } while (0)
; #define PG8_MMA(ai, bj, At, Bt) do { __builtin_amdgcn_s_setprio(1); _Pragma("unroll") for (int m = 0; m < 4; ++m) _Pragma("unroll") for (int n = 0; n < 2; ++n) _Pragma("unroll") for (int k = 0; k < 2; ++k) \
;         acc[ai][bj][m][n] = __builtin_amdgcn_mfma_f32_16x16x32_bf16(Bt[n][k], At[m][k], acc[ai][bj][m][n], 0, 0, 0); __builtin_amdgcn_s_setprio(0); } while (0)
; #define PG8_WAIT_V89() do { if constexpr (SLIVER) PG8_WAIT_V(9); else PG8_WAIT_V(8); } while (0)
; #define PG8_WAIT_L(n) asm volatile("s_waitcnt lgkmcnt(" #n ")" ::: "memory")
; #define PG8_BAR __builtin_amdgcn_s_barrier()
; template <class Epi, class Sched, bool ALIGN_EPI = false, bool SP2 = false, bool SLIVER = false>
; __device__ __forceinline__ void gemm_phase(PG8_LAS unsigned char* lds, const Gemm g, const Sched& S, const Epi& E) {
;     ...
;         for (int t = 0; t < nt; t += 2) {
;             const bool last = (t == nt - 2);
;             const char* a1 = cA + (size_t)(t + 1) * kstep;
;             const char* a2 = last ? nA : cA + (size_t)(t + 2) * kstep; const char* b2 = last ? nB : cB + (size_t)(t + 2) * kstep;
;             const char* a3 = a2 + kstep; const char* b3 = b2 + kstep;
;             const char* s1 = cS + (size_t)(t + 1) * kstep; const char* s2 = last ? nS : cS + (size_t)(t + 2) * kstep;
;             if (last && has_next) S.a_ready(nxt);
;             if constexpr (SP2) {
;             PG8_LDB(B0, 0, 0); PG8_LDB(B1, 0, 1); PG8_SCHED; PG8_LDA(At, 0, 0); PG8_STAGE(PG8_SA(1, 1), a1 + hstep, voffA); PG8_STAGE_S(1, s1);
;             PG8_WAIT_V89(); PG8_WAIT_L(0); PG8_BAR; PG8_MMA(0, 0, At, B0); PG8_MMA(0, 1, At, B1); PG8_BAR; PG8_SCHED;
.LBB0_705:
	s_add_u32 s76, s62, 0xfff80080
	s_addc_u32 s77, s63, -1
	s_add_i32 s78, 0, 0x10000
	s_cmp_eq_u32 s69, 28
	s_cselect_b32 s81, s3, s77
	s_cselect_b32 s80, s51, s76
	v_add_u32_e32 v142, s78, v143
	s_cselect_b32 s77, s49, s68
	s_cselect_b32 s76, s66, s67
	s_add_i32 s79, 0, 0x14000
	ds_read_b128 v[130:133], v142
	ds_read_b128 v[138:141], v142 offset:1024
	ds_read_b128 v[148:151], v142 offset:2048
	ds_read_b128 v[152:155], v142 offset:3072
	v_add_u32_e32 v142, s79, v143
	ds_read_b128 v[156:159], v142
	ds_read_b128 v[160:163], v142 offset:1024
	ds_read_b128 v[164:167], v142 offset:2048
	ds_read_b128 v[168:171], v142 offset:3072
	s_mov_b64 s[46:47], s[62:63]
	s_add_i32 m0, s45, 0xc000
	ds_read_b128 v[172:175], v147
	ds_read_b128 v[180:183], v147 offset:1024
	ds_read_b128 v[184:187], v147 offset:2048
	ds_read_b128 v[188:191], v147 offset:3072
	ds_read_b128 v[192:195], v147 offset:4096
	ds_read_b128 v[196:199], v147 offset:5120
	ds_read_b128 v[200:203], v147 offset:6144
	ds_read_b128 v[210:213], v147 offset:7168
	s_cmp_eq_u32 s69, s101
	s_cbranch_scc1 .Lgup_skipw0
	global_load_lds_dwordx4 v136, s[46:47]
	s_add_i32 m0, s45, 0xe000
	s_nop 0
	s_add_u32 s36, s46, 0x40000
	s_addc_u32 s37, s47, 0
	global_load_lds_dwordx4 v136, s[36:37]
	s_waitcnt vmcnt(8)

; #define PG8_SB(B) __builtin_amdgcn_rcpf(1.f + expneg(B))
; #define PG8_SB(B) __builtin_amdgcn_rcpf(1.f + expneg(B))
; #define PG8_STAGE(bufoff, gbase, voff) do { _Pragma("unroll") for (int _i = 0; _i < 2; ++_i) \
;         __builtin_amdgcn_global_load_lds((const unsigned*)((const char*)(gbase) + (size_t)_i * qstep + (voff)[0]), (PG8_LAS unsigned*)(lds + (bufoff) + ldsw + _i * 8192), 16, 0, 0); } while (0)
; #define PG8_LDA(dst, b, h) do { _Pragma("unroll") for (int m = 0; m < 4; ++m) _Pragma("unroll") for (int k = 0; k < 2; ++k) dst[m][k] = *(const PG8_LAS bf16x8*)(lds + PG8_SA(b, h) + aoff + m * 2048 + k * 1024); } while (0)
; #define PG8_LDB(dst, b, h) do { _Pragma("unroll") for (int n = 0; n < 2; ++n) _Pragma("unroll") for (int k = 0; k < 2; ++k) dst[n][k] = *(const PG8_LAS bf16x8*)(lds + PG8_SB(b, h) + boff + n * 2048 + k * 1024); } while (0)
; #define PG8_MMA(ai, bj, At, Bt) do { __builtin_amdgcn_s_setprio(1); _Pragma("unroll") for (int m = 0; m < 4; ++m) _Pragma("unroll") for (int n = 0; n < 2; ++n) _Pragma("unroll") for (int k = 0; k < 2; ++k) \
;         acc[ai][bj][m][n] = __builtin_amdgcn_mfma_f32_16x16x32_bf16(Bt[n][k], At[m][k], acc[ai][bj][m][n], 0, 0, 0); __builtin_amdgcn_s_setprio(0); } while (0)
; #define PG8_WAIT_V89() do { if constexpr (SLIVER) PG8_WAIT_V(9); else PG8_WAIT_V(8); } while (0)
; #define PG8_WAIT_L(n) asm volatile("s_waitcnt lgkmcnt(" #n ")" ::: "memory")
; #define PG8_BAR __builtin_amdgcn_s_barrier()
; template <class Epi, class Sched, bool ALIGN_EPI = false, bool SP2 = false, bool SLIVER = false>
; __device__ __forceinline__ void gemm_phase(PG8_LAS unsigned char* lds, const Gemm g, const Sched& S, const Epi& E) {
;     ...
;             PG8_WAIT_V89(); PG8_WAIT_L(0); PG8_BAR; PG8_MMA(0, 0, At, B0); PG8_MMA(0, 1, At, B1); PG8_BAR; PG8_SCHED;
;             PG8_LDA(At, 0, 1); PG8_LDS_S(0); PG8_STAGE(PG8_SB(0, 0), b2, voffB); PG8_STAGE(PG8_SB(0, 1), b2 + hstep, voffB); PG8_STAGE(PG8_SA(0, 0), a2, voffA);
;             PG8_WAIT_V89(); PG8_WAIT_L(0); PG8_BAR; PG8_MMA(1, 0, At, B0); PG8_MMA(1, 1, At, B1); PG8_MMA_S(); PG8_BAR; PG8_SCHED;
;             PG8_LDB(B0, 1, 0); PG8_LDB(B1, 1, 1); PG8_SCHED; PG8_LDA(At, 1, 0); PG8_STAGE(PG8_SA(0, 1), a2 + hstep, voffA); PG8_STAGE_S(0, s2);
;             PG8_WAIT_V89(); PG8_WAIT_L(0); PG8_BAR; PG8_MMA(0, 0, At, B0); PG8_MMA(0, 1, At, B1); PG8_BAR; PG8_SCHED;
.Lgup_skipw1:
	s_waitcnt lgkmcnt(0)
	s_setprio 1
	s_barrier
	v_mfma_f32_16x16x32_bf16 v[62:65], v[130:133], v[172:175], v[62:65]
	v_mfma_f32_16x16x32_bf16 v[54:57], v[148:151], v[172:175], v[54:57]
	v_mfma_f32_16x16x32_bf16 v[46:49], v[130:133], v[184:187], v[46:49]
	v_mfma_f32_16x16x32_bf16 v[38:41], v[148:151], v[184:187], v[38:41]
	v_mfma_f32_16x16x32_bf16 v[30:33], v[130:133], v[192:195], v[30:33]
	v_mfma_f32_16x16x32_bf16 v[22:25], v[148:151], v[192:195], v[22:25]
	v_mfma_f32_16x16x32_bf16 v[14:17], v[130:133], v[200:203], v[14:17]
	v_mfma_f32_16x16x32_bf16 v[6:9], v[148:151], v[200:203], v[6:9]
	v_mfma_f32_16x16x32_bf16 v[62:65], v[138:141], v[180:183], v[62:65]
	v_mfma_f32_16x16x32_bf16 v[54:57], v[152:155], v[180:183], v[54:57]
	v_mfma_f32_16x16x32_bf16 v[46:49], v[138:141], v[188:191], v[46:49]
	v_mfma_f32_16x16x32_bf16 v[38:41], v[152:155], v[188:191], v[38:41]
	v_mfma_f32_16x16x32_bf16 v[30:33], v[138:141], v[196:199], v[30:33]
	v_mfma_f32_16x16x32_bf16 v[22:25], v[152:155], v[196:199], v[22:25]
	v_mfma_f32_16x16x32_bf16 v[14:17], v[138:141], v[210:213], v[14:17]
	v_mfma_f32_16x16x32_bf16 v[6:9], v[152:155], v[210:213], v[6:9]
	s_setprio 0
	s_setprio 1
	v_mfma_f32_16x16x32_bf16 v[58:61], v[156:159], v[172:175], v[58:61]
	v_mfma_f32_16x16x32_bf16 v[50:53], v[164:167], v[172:175], v[50:53]
	v_mfma_f32_16x16x32_bf16 v[42:45], v[156:159], v[184:187], v[42:45]
	v_mfma_f32_16x16x32_bf16 v[34:37], v[164:167], v[184:187], v[34:37]
	v_mfma_f32_16x16x32_bf16 v[26:29], v[156:159], v[192:195], v[26:29]
	v_mfma_f32_16x16x32_bf16 v[18:21], v[164:167], v[192:195], v[18:21]
	v_mfma_f32_16x16x32_bf16 v[10:13], v[156:159], v[200:203], v[10:13]
	v_mfma_f32_16x16x32_bf16 v[2:5], v[164:167], v[200:203], v[2:5]
	v_mfma_f32_16x16x32_bf16 v[58:61], v[160:163], v[180:183], v[58:61]
	v_mfma_f32_16x16x32_bf16 v[50:53], v[168:171], v[180:183], v[50:53]
	v_mfma_f32_16x16x32_bf16 v[42:45], v[160:163], v[188:191], v[42:45]
	v_mfma_f32_16x16x32_bf16 v[34:37], v[168:171], v[188:191], v[34:37]
	v_mfma_f32_16x16x32_bf16 v[26:29], v[160:163], v[196:199], v[26:29]
	v_mfma_f32_16x16x32_bf16 v[18:21], v[168:171], v[196:199], v[18:21]
	v_mfma_f32_16x16x32_bf16 v[10:13], v[160:163], v[210:213], v[10:13]
	v_mfma_f32_16x16x32_bf16 v[2:5], v[168:171], v[210:213], v[2:5]
	s_barrier
	s_setprio 0
	s_add_i32 s76, 0, 0x18000
	v_add_u32_e32 v142, s76, v143
	s_add_i32 s77, 0, 0x1c000
	ds_read_b128 v[130:133], v142
	ds_read_b128 v[138:141], v142 offset:1024
	ds_read_b128 v[148:151], v142 offset:2048
	ds_read_b128 v[152:155], v142 offset:3072
	v_add_u32_e32 v142, s77, v143
	ds_read_b128 v[156:159], v142
	ds_read_b128 v[160:163], v142 offset:1024
	ds_read_b128 v[164:167], v142 offset:2048
	ds_read_b128 v[168:171], v142 offset:3072
	s_mov_b32 m0, s90
	ds_read_b128 v[172:175], v147 offset:32768
	ds_read_b128 v[180:183], v147 offset:33792
	ds_read_b128 v[184:187], v147 offset:34816
	ds_read_b128 v[188:191], v147 offset:35840
	ds_read_b128 v[192:195], v147 offset:36864
	ds_read_b128 v[196:199], v147 offset:37888
	ds_read_b128 v[200:203], v147 offset:38912
	ds_read_b128 v[210:213], v147 offset:39936
	s_add_u32 s60, s80, 0x80000
	s_addc_u32 s61, s81, 0
	global_load_lds_dwordx4 v134, s[60:61]
	s_mov_b32 m0, s91
	s_nop 0
	s_add_u32 s36, s80, 0xc0000
	s_addc_u32 s37, s81, 0
	global_load_lds_dwordx4 v134, s[36:37]
	s_cmp_eq_u32 s69, s101
	s_cbranch_scc1 .Lgup_skipw2
	s_waitcnt vmcnt(8)
.Lgup_skipw2:
	s_waitcnt lgkmcnt(0)
	s_setprio 1
	s_barrier
	v_mfma_f32_16x16x32_bf16 v[126:129], v[130:133], v[172:175], v[126:129]
	v_mfma_f32_16x16x32_bf16 v[118:121], v[148:151], v[172:175], v[118:121]
	v_mfma_f32_16x16x32_bf16 v[110:113], v[130:133], v[184:187], v[110:113]
	v_mfma_f32_16x16x32_bf16 v[102:105], v[148:151], v[184:187], v[102:105]
	v_mfma_f32_16x16x32_bf16 v[94:97], v[130:133], v[192:195], v[94:97]
	v_mfma_f32_16x16x32_bf16 v[86:89], v[148:151], v[192:195], v[86:89]
	v_mfma_f32_16x16x32_bf16 v[78:81], v[130:133], v[200:203], v[78:81]
	v_mfma_f32_16x16x32_bf16 v[70:73], v[148:151], v[200:203], v[70:73]
	v_mfma_f32_16x16x32_bf16 v[126:129], v[138:141], v[180:183], v[126:129]
	v_mfma_f32_16x16x32_bf16 v[118:121], v[152:155], v[180:183], v[118:121]
	v_mfma_f32_16x16x32_bf16 v[110:113], v[138:141], v[188:191], v[110:113]
	v_mfma_f32_16x16x32_bf16 v[102:105], v[152:155], v[188:191], v[102:105]
	v_mfma_f32_16x16x32_bf16 v[94:97], v[138:141], v[196:199], v[94:97]
	v_mfma_f32_16x16x32_bf16 v[86:89], v[152:155], v[196:199], v[86:89]
	v_mfma_f32_16x16x32_bf16 v[78:81], v[138:141], v[210:213], v[78:81]
	v_mfma_f32_16x16x32_bf16 v[70:73], v[152:155], v[210:213], v[70:73]
	s_setprio 0
	s_setprio 1
	v_mfma_f32_16x16x32_bf16 v[122:125], v[156:159], v[172:175], v[122:125]
	v_mfma_f32_16x16x32_bf16 v[114:117], v[164:167], v[172:175], v[114:117]
	v_mfma_f32_16x16x32_bf16 v[106:109], v[156:159], v[184:187], v[106:109]
	v_mfma_f32_16x16x32_bf16 v[98:101], v[164:167], v[184:187], v[98:101]
	v_mfma_f32_16x16x32_bf16 v[90:93], v[156:159], v[192:195], v[90:93]
	v_mfma_f32_16x16x32_bf16 v[82:85], v[164:167], v[192:195], v[82:85]
	v_mfma_f32_16x16x32_bf16 v[74:77], v[156:159], v[200:203], v[74:77]
	v_mfma_f32_16x16x32_bf16 v[66:69], v[164:167], v[200:203], v[66:69]
	v_mfma_f32_16x16x32_bf16 v[122:125], v[160:163], v[180:183], v[122:125]
	v_mfma_f32_16x16x32_bf16 v[114:117], v[168:171], v[180:183], v[114:117]
	v_mfma_f32_16x16x32_bf16 v[106:109], v[160:163], v[188:191], v[106:109]
	v_mfma_f32_16x16x32_bf16 v[98:101], v[168:171], v[188:191], v[98:101]
	v_mfma_f32_16x16x32_bf16 v[90:93], v[160:163], v[196:199], v[90:93]
	v_mfma_f32_16x16x32_bf16 v[82:85], v[168:171], v[196:199], v[82:85]
	v_mfma_f32_16x16x32_bf16 v[74:77], v[160:163], v[210:213], v[74:77]
	v_mfma_f32_16x16x32_bf16 v[66:69], v[168:171], v[210:213], v[66:69]
	s_barrier
; #define PG8_SB(B) __builtin_amdgcn_rcpf(1.f + expneg(B))
; #define PG8_SB(B) __builtin_amdgcn_rcpf(1.f + expneg(B))
; #define PG8_STAGE(bufoff, gbase, voff) do { _Pragma("unroll") for (int _i = 0; _i < 2; ++_i) \
;         __builtin_amdgcn_global_load_lds((const unsigned*)((const char*)(gbase) + (size_t)_i * qstep + (voff)[0]), (PG8_LAS unsigned*)(lds + (bufoff) + ldsw + _i * 8192), 16, 0, 0); } while (0)
; #define PG8_LDA(dst, b, h) do { _Pragma("unroll") for (int m = 0; m < 4; ++m) _Pragma("unroll") for (int k = 0; k < 2; ++k) dst[m][k] = *(const PG8_LAS bf16x8*)(lds + PG8_SA(b, h) + aoff + m * 2048 + k * 1024); } while (0)
; #define PG8_LDB(dst, b, h) do { _Pragma("unroll") for (int n = 0; n < 2; ++n) _Pragma("unroll") for (int k = 0; k < 2; ++k) dst[n][k] = *(const PG8_LAS bf16x8*)(lds + PG8_SB(b, h) + boff + n * 2048 + k * 1024); } while (0)
; #define PG8_WAIT_V89() do { if constexpr (SLIVER) PG8_WAIT_V(9); else PG8_WAIT_V(8); } while (0)
; #define PG8_WAIT_L(n) asm volatile("s_waitcnt lgkmcnt(" #n ")" ::: "memory")
; template <class Epi, class Sched, bool ALIGN_EPI = false, bool SP2 = false, bool SLIVER = false>
; __device__ __forceinline__ void gemm_phase(PG8_LAS unsigned char* lds, const Gemm g, const Sched& S, const Epi& E) {
;     ...
;             PG8_LDB(B0, 1, 0); PG8_LDB(B1, 1, 1); PG8_SCHED; PG8_LDA(At, 1, 0); PG8_STAGE(PG8_SA(0, 1), a2 + hstep, voffA); PG8_STAGE_S(0, s2);
;             PG8_WAIT_V89(); PG8_WAIT_L(0); PG8_BAR; PG8_MMA(0, 0, At, B0); PG8_MMA(0, 1, At, B1); PG8_BAR; PG8_SCHED;
;             PG8_LDA(At, 1, 1); PG8_LDS_S(1); PG8_STAGE(PG8_SB(1, 0), b3, voffB); PG8_STAGE(PG8_SB(1, 1), b3 + hstep, voffB); PG8_STAGE(PG8_SA(1, 0), a3, voffA);
;             PG8_WAIT_V89(); PG8_WAIT_L(0); PG8_BAR; PG8_MMA(1, 0, At, B0); PG8_MMA(1, 1, At, B1); PG8_MMA_S(); PG8_BAR; PG8_SCHED;
;     ...
;         if constexpr (ALIGN_EPI) { if (wr == 0) PG8_BAR; }
;         const bool fin = Epi::final_seg(cur.seg);
;         if constexpr (!Epi::AFTER_DRAIN) { int l2_ = threadIdx.x; asm volatile("" : "+v"(l2_)); const int fr2 = l2_ & 15, fq2 = (l2_ >> 4) & 3;
;             if (fin) { E(acc, cur, wr, wc, fr2, fq2); if constexpr (SLIVER) E.sliver(accs, cur, S.srow0, wr, wc, fr2, fq2); E.finish(cur, S.srow0, l2_); } else { E.mid(acc, cur, wr, wc, fr2, fq2); if constexpr (SLIVER) E.sliver_mid(accs, cur, S.srow0, wr, wc, fr2, fq2); } S.done(cur); }
	s_setprio 0
	s_add_i32 s76, s76, s88
	s_mov_b32 m0, s76
	ds_read_b128 v[172:175], v147 offset:49152
	ds_read_b128 v[180:183], v147 offset:50176
	ds_read_b128 v[184:187], v147 offset:51200
	ds_read_b128 v[188:191], v147 offset:52224
	ds_read_b128 v[192:195], v147 offset:53248
	ds_read_b128 v[196:199], v147 offset:54272
	ds_read_b128 v[200:203], v147 offset:55296
	ds_read_b128 v[210:213], v147 offset:56320
	s_add_u32 s58, s46, 0x80
	s_addc_u32 s59, s47, 0
	global_load_lds_dwordx4 v178, s[58:59]
	s_add_i32 m0, s76, 0x2000
	s_add_i32 s76, s77, s88
	s_add_u32 s60, s46, 0x40080
	s_addc_u32 s61, s47, 0
	global_load_lds_dwordx4 v178, s[60:61]
	s_mov_b32 m0, s76
	s_add_u32 s36, s46, 0x80080
	s_addc_u32 s37, s47, 0
	global_load_lds_dwordx4 v178, s[36:37]
	s_add_i32 m0, s76, 0x2000
	s_nop 0
	s_add_u32 s58, s46, 0xc0080
	s_addc_u32 s59, s47, 0
	global_load_lds_dwordx4 v178, s[58:59]
	s_mov_b32 m0, s93
	s_nop 0
	s_add_u32 s60, s80, 0x80
	s_addc_u32 s61, s81, 0
	global_load_lds_dwordx4 v134, s[60:61]
	s_mov_b32 m0, s94
	s_nop 0
	s_add_u32 s36, s80, 0x40080
	s_addc_u32 s37, s81, 0
	global_load_lds_dwordx4 v134, s[36:37]
	s_waitcnt vmcnt(8)
	s_waitcnt lgkmcnt(0)
	s_setprio 1
	s_barrier
	v_mfma_f32_16x16x32_bf16 v[62:65], v[130:133], v[172:175], v[62:65]
	v_mfma_f32_16x16x32_bf16 v[54:57], v[148:151], v[172:175], v[54:57]
	v_mfma_f32_16x16x32_bf16 v[46:49], v[130:133], v[184:187], v[46:49]
	v_mfma_f32_16x16x32_bf16 v[38:41], v[148:151], v[184:187], v[38:41]
	v_mfma_f32_16x16x32_bf16 v[30:33], v[130:133], v[192:195], v[30:33]
	v_mfma_f32_16x16x32_bf16 v[22:25], v[148:151], v[192:195], v[22:25]
	v_mfma_f32_16x16x32_bf16 v[14:17], v[130:133], v[200:203], v[14:17]
	v_mfma_f32_16x16x32_bf16 v[6:9], v[148:151], v[200:203], v[6:9]
	v_mfma_f32_16x16x32_bf16 v[62:65], v[138:141], v[180:183], v[62:65]
	v_mfma_f32_16x16x32_bf16 v[54:57], v[152:155], v[180:183], v[54:57]
	v_mfma_f32_16x16x32_bf16 v[46:49], v[138:141], v[188:191], v[46:49]
	v_mfma_f32_16x16x32_bf16 v[38:41], v[152:155], v[188:191], v[38:41]
	v_mfma_f32_16x16x32_bf16 v[30:33], v[138:141], v[196:199], v[30:33]
	v_mfma_f32_16x16x32_bf16 v[22:25], v[152:155], v[196:199], v[22:25]
	v_mfma_f32_16x16x32_bf16 v[14:17], v[138:141], v[210:213], v[14:17]
	v_mfma_f32_16x16x32_bf16 v[6:9], v[152:155], v[210:213], v[6:9]
	s_setprio 0
	s_setprio 1
	v_mfma_f32_16x16x32_bf16 v[58:61], v[156:159], v[172:175], v[58:61]
	v_mfma_f32_16x16x32_bf16 v[50:53], v[164:167], v[172:175], v[50:53]
	v_mfma_f32_16x16x32_bf16 v[42:45], v[156:159], v[184:187], v[42:45]
	v_mfma_f32_16x16x32_bf16 v[34:37], v[164:167], v[184:187], v[34:37]
	v_mfma_f32_16x16x32_bf16 v[26:29], v[156:159], v[192:195], v[26:29]
	v_mfma_f32_16x16x32_bf16 v[18:21], v[164:167], v[192:195], v[18:21]
	v_mfma_f32_16x16x32_bf16 v[10:13], v[156:159], v[200:203], v[10:13]
	v_mfma_f32_16x16x32_bf16 v[2:5], v[164:167], v[200:203], v[2:5]
	v_mfma_f32_16x16x32_bf16 v[58:61], v[160:163], v[180:183], v[58:61]
	v_mfma_f32_16x16x32_bf16 v[50:53], v[168:171], v[180:183], v[50:53]
	v_mfma_f32_16x16x32_bf16 v[42:45], v[160:163], v[188:191], v[42:45]
	v_mfma_f32_16x16x32_bf16 v[34:37], v[168:171], v[188:191], v[34:37]
	v_mfma_f32_16x16x32_bf16 v[26:29], v[160:163], v[196:199], v[26:29]
	v_mfma_f32_16x16x32_bf16 v[18:21], v[168:171], v[196:199], v[18:21]
	v_mfma_f32_16x16x32_bf16 v[10:13], v[160:163], v[210:213], v[10:13]
	v_mfma_f32_16x16x32_bf16 v[2:5], v[168:171], v[210:213], v[2:5]
	s_barrier
	s_setprio 0
	s_add_i32 s69, s69, 2
	s_add_u32 s62, s62, 0x100
	s_addc_u32 s63, s63, 0
	s_add_u32 s67, s67, 0x100
	s_addc_u32 s68, s68, 0
	s_cmp_gt_u32 s69, 29
	s_cbranch_scc0 .LBB0_705
	s_and_b64 vcc, exec, s[42:43]
	s_cbranch_vccz .LBB0_708
	s_barrier
.LBB0_708:
	s_add_u32 s36, s51, 0x80080
	s_addc_u32 s37, s3, 0
	s_add_i32 m0, s45, 0xc000
	s_nop 0
	global_load_lds_dwordx4 v136, s[36:37]
	s_add_u32 s36, s36, 0x40000
	s_addc_u32 s37, s37, 0
	s_add_i32 m0, s45, 0xe000
	s_nop 0
	global_load_lds_dwordx4 v136, s[36:37]
	s_lshl_b32 s3, s82, 8
	v_mov_b32_e32 v130, v0
	s_add_i32 s3, s3, s10
	s_lshl_b32 s2, s2, 7
	v_and_or_b32 v164, v130, 15, s3
	v_ashrrev_i32_e32 v165, 31, v164
	v_lshrrev_b32_e32 v151, 1, v130
	v_mov_b32_e32 v210, v214
	v_mov_b32_e32 v211, v215
	v_mov_b32_e32 v212, v216
	v_mov_b32_e32 v213, v217
	v_or_b32_e32 v160, 16, v164
	v_ashrrev_i32_e32 v161, 31, v160
	v_or_b32_e32 v156, 32, v164
	v_ashrrev_i32_e32 v157, 31, v156
	v_or_b32_e32 v152, 48, v164
	v_ashrrev_i32_e32 v153, 31, v152
	v_add_u32_e32 v148, 0x80, v164
	v_ashrrev_i32_e32 v149, 31, v148
	v_add_u32_e32 v144, 0x90, v164
	v_ashrrev_i32_e32 v145, 31, v144
	v_mov_b32_e32 v180, v218
	v_mov_b32_e32 v181, v219
	v_mov_b32_e32 v182, v220
	v_mov_b32_e32 v183, v221
	v_mov_b32_e32 v184, v222
	v_mov_b32_e32 v185, v223
	v_mov_b32_e32 v186, v224
	v_mov_b32_e32 v187, v225
	v_mov_b32_e32 v188, v226
	v_mov_b32_e32 v189, v227
	v_mov_b32_e32 v190, v228
	v_mov_b32_e32 v191, v229
	v_mov_b32_e32 v192, v230
	v_mov_b32_e32 v193, v231
	v_mov_b32_e32 v194, v232
	v_mov_b32_e32 v195, v233
	v_mov_b32_e32 v196, v240
	v_mov_b32_e32 v197, v241
	v_mov_b32_e32 v198, v242
	v_mov_b32_e32 v199, v243
	v_mov_b32_e32 v200, v244
	v_mov_b32_e32 v201, v245
	v_mov_b32_e32 v202, v246
	v_mov_b32_e32 v203, v247
	v_mov_b32_e32 v130, v248
	v_mov_b32_e32 v131, v249
	v_mov_b32_e32 v132, v250
	v_mov_b32_e32 v133, v251
	s_movk_i32 s49, 0x2c00
	s_mov_b64 s[62:63], -1
	s_andn2_b64 vcc, exec, s[38:39]
	v_readlane_b32 s79, v254, 35
	s_movk_i32 s77, 0x70
	s_mov_b64 s[68:69], 0x4000c00
	s_waitcnt vmcnt(7)
; __device__ __forceinline__ u32x4 pack8(const f32x4& a, const f32x4& b) { u32x4 w; w.x = cvt_pk_bf16(a[0], a[1]); w.y = cvt_pk_bf16(a[2], a[3]); w.z = cvt_pk_bf16(b[0], b[1]); w.w = cvt_pk_bf16(b[2], b[3]); return w; }
; __device__ __forceinline__ float expneg(float g) { return ex2(fminf(-g * 1.4426950408889634f, 80.f)); }
; __device__ __forceinline__ float ss_total(const u32x4 a) { return ((bflo(a.x) + bfhi(a.x)) + (bflo(a.y) + bfhi(a.y))) + ((bflo(a.z) + bfhi(a.z)) + (bflo(a.w) + bfhi(a.w))); }
; __device__ __forceinline__ float row_rstd(const bf16_t* ss, int row) { const u32x4 a = *(const u32x4*)(ss + (size_t)row * 8);
;     return __builtin_amdgcn_rsqf(ss_total(a) * (1.f / 2048.f) + 1e-6f); }
;     __device__ __forceinline__ void operator()(const f32x4 (&acc)[2][2][4][2], const Unit& u, int wr, int wc, int fr, int fq) const {
;         const int rowt = u.pm * BM + wr * 64 + fr, col0 = u.pn * HALF + wc * 32 + 8 * fq;
;         float rsv[2][4];
; #pragma unroll
;         for (int ai = 0; ai < 2; ++ai)
; #pragma unroll
;             for (int m = 0; m < 4; ++m) rsv[ai][m] = row_rstd(ss, rowt + ai * HALF + m * 16);
; #pragma unroll
;         for (int ai = 0; ai < 2; ++ai)
; #pragma unroll
;             for (int m = 0; m < 4; ++m) { f32x4 v[2]; const float rs = rsv[ai][m];
; #pragma unroll
;                 for (int n = 0; n < 2; ++n)
; #pragma unroll
;                     for (int i = 0; i < 4; ++i) { const float g = acc[ai][0][m][n][i] * rs; v[n][i] = g * __builtin_amdgcn_rcpf(1.f + expneg(g)) * (acc[ai][1][m][n][i] * rs); }
;                 *(u32x4*)(act + (size_t)(rowt + ai * HALF + m * 16) * 5632 + col0) = pack8(v[0], v[1]); }
	v_lshlrev_b32_e32 v139, 16, v212
	v_lshlrev_b32_e32 v138, 16, v210
	v_and_b32_e32 v141, 0xffff0000, v212
	v_and_b32_e32 v140, 0xffff0000, v210
	v_pk_add_f32 v[138:139], v[138:139], v[140:141]
	v_lshlrev_b32_e32 v141, 16, v213
	v_lshlrev_b32_e32 v140, 16, v211
	v_and_b32_e32 v213, 0xffff0000, v213
	v_and_b32_e32 v212, 0xffff0000, v211
	v_pk_add_f32 v[210:211], v[140:141], v[212:213]
	s_nop 0
	v_pk_add_f32 v[210:211], v[138:139], v[210:211]
	s_nop 0
	v_add_f32_e32 v210, v210, v211
	v_fmamk_f32 v210, v210, 0x3a000000, v1
	v_rsq_f32_e32 v166, v210
	s_waitcnt vmcnt(6)
	v_lshlrev_b32_e32 v139, 16, v182
	v_lshlrev_b32_e32 v138, 16, v180
	v_and_b32_e32 v141, 0xffff0000, v182
	v_and_b32_e32 v140, 0xffff0000, v180
	v_pk_add_f32 v[138:139], v[138:139], v[140:141]
	v_lshlrev_b32_e32 v141, 16, v183
	v_lshlrev_b32_e32 v140, 16, v181
	v_and_b32_e32 v183, 0xffff0000, v183
	v_and_b32_e32 v182, 0xffff0000, v181
	v_pk_add_f32 v[180:181], v[140:141], v[182:183]
	s_nop 0
	v_pk_add_f32 v[180:181], v[138:139], v[180:181]
	s_nop 0
	v_add_f32_e32 v180, v180, v181
	v_fmamk_f32 v180, v180, 0x3a000000, v1
	v_rsq_f32_e32 v162, v180
	s_waitcnt vmcnt(5)
	v_lshlrev_b32_e32 v139, 16, v186
	v_lshlrev_b32_e32 v138, 16, v184
	v_and_b32_e32 v141, 0xffff0000, v186
	v_and_b32_e32 v140, 0xffff0000, v184
	v_pk_add_f32 v[138:139], v[138:139], v[140:141]
	v_lshlrev_b32_e32 v141, 16, v187
	v_lshlrev_b32_e32 v140, 16, v185
	v_and_b32_e32 v187, 0xffff0000, v187
	v_and_b32_e32 v186, 0xffff0000, v185
	v_pk_add_f32 v[184:185], v[140:141], v[186:187]
	s_nop 0
	v_pk_add_f32 v[184:185], v[138:139], v[184:185]
	s_nop 0
	v_add_f32_e32 v184, v184, v185
	v_fmamk_f32 v184, v184, 0x3a000000, v1
	v_rsq_f32_e32 v158, v184
	s_waitcnt vmcnt(4)
	v_lshlrev_b32_e32 v139, 16, v190
	v_lshlrev_b32_e32 v138, 16, v188
	v_and_b32_e32 v141, 0xffff0000, v190
	v_and_b32_e32 v140, 0xffff0000, v188
	v_pk_add_f32 v[138:139], v[138:139], v[140:141]
	v_lshlrev_b32_e32 v141, 16, v191
	v_lshlrev_b32_e32 v140, 16, v189
	v_and_b32_e32 v191, 0xffff0000, v191
	v_and_b32_e32 v190, 0xffff0000, v189
	v_pk_add_f32 v[188:189], v[140:141], v[190:191]
	s_nop 0
	v_pk_add_f32 v[188:189], v[138:139], v[188:189]
	s_nop 0
	v_add_f32_e32 v188, v188, v189
	v_fmamk_f32 v188, v188, 0x3a000000, v1
	v_rsq_f32_e32 v154, v188
	s_waitcnt vmcnt(3)
	v_lshlrev_b32_e32 v139, 16, v194
	v_lshlrev_b32_e32 v138, 16, v192
	v_and_b32_e32 v141, 0xffff0000, v194
	v_and_b32_e32 v140, 0xffff0000, v192
	v_pk_add_f32 v[138:139], v[138:139], v[140:141]
	v_lshlrev_b32_e32 v141, 16, v195
	v_lshlrev_b32_e32 v140, 16, v193
	v_and_b32_e32 v195, 0xffff0000, v195
	v_and_b32_e32 v194, 0xffff0000, v193
	v_pk_add_f32 v[192:193], v[140:141], v[194:195]
	s_nop 0
	v_pk_add_f32 v[192:193], v[138:139], v[192:193]
	s_nop 0
	v_add_f32_e32 v192, v192, v193
	v_fmamk_f32 v192, v192, 0x3a000000, v1
	v_rsq_f32_e32 v150, v192
	s_waitcnt vmcnt(2)
	v_lshlrev_b32_e32 v139, 16, v198
	v_lshlrev_b32_e32 v138, 16, v196
	v_and_b32_e32 v141, 0xffff0000, v198
	v_and_b32_e32 v140, 0xffff0000, v196
	v_pk_add_f32 v[138:139], v[138:139], v[140:141]
	v_lshlrev_b32_e32 v141, 16, v199
	v_lshlrev_b32_e32 v140, 16, v197
	v_and_b32_e32 v199, 0xffff0000, v199
	v_and_b32_e32 v198, 0xffff0000, v197
	v_pk_add_f32 v[196:197], v[140:141], v[198:199]
	v_add_u32_e32 v140, 0xa0, v164
	v_pk_add_f32 v[196:197], v[138:139], v[196:197]
	v_ashrrev_i32_e32 v141, 31, v140
	v_add_f32_e32 v196, v196, v197
	v_fmamk_f32 v196, v196, 0x3a000000, v1
	v_rsq_f32_e32 v146, v196
	s_waitcnt vmcnt(1)
	v_lshlrev_b32_e32 v139, 16, v202
	v_lshlrev_b32_e32 v138, 16, v200
	v_and_b32_e32 v169, 0xffff0000, v202
	v_and_b32_e32 v168, 0xffff0000, v200
	v_pk_add_f32 v[138:139], v[138:139], v[168:169]
	v_lshlrev_b32_e32 v169, 16, v203
	v_lshlrev_b32_e32 v168, 16, v201
	v_and_b32_e32 v203, 0xffff0000, v203
	v_and_b32_e32 v202, 0xffff0000, v201
	v_pk_add_f32 v[200:201], v[168:169], v[202:203]
	s_nop 0
	v_pk_add_f32 v[200:201], v[138:139], v[200:201]
	v_add_u32_e32 v138, 0xb0, v164
	v_add_f32_e32 v200, v200, v201
	v_fmamk_f32 v200, v200, 0x3a000000, v1
	v_ashrrev_i32_e32 v139, 31, v138
	v_rsq_f32_e32 v142, v200
	s_waitcnt vmcnt(0)
	v_lshlrev_b32_e32 v169, 16, v132
	v_lshlrev_b32_e32 v168, 16, v130
	v_and_b32_e32 v171, 0xffff0000, v132
	v_and_b32_e32 v170, 0xffff0000, v130
	v_pk_add_f32 v[168:169], v[168:169], v[170:171]
	v_lshlrev_b32_e32 v171, 16, v133
	v_lshlrev_b32_e32 v170, 16, v131
	v_and_b32_e32 v133, 0xffff0000, v133
	v_and_b32_e32 v132, 0xffff0000, v131
	v_pk_add_f32 v[130:131], v[170:171], v[132:133]
	s_nop 0
	v_pk_add_f32 v[130:131], v[168:169], v[130:131]
	v_mov_b32_e32 v168, v122
	v_mov_b32_e32 v169, v126
	v_pk_mul_f32 v[168:169], v[168:169], v[166:167] op_sel_hi:[1,0]
	v_add_f32_e32 v130, v130, v131
	v_mul_f32_e32 v122, 0xbfb8aa3b, v169
	v_min_f32_e32 v122, 0x42a00000, v122
	v_exp_f32_e32 v122, v122
	v_and_or_b32 v131, v151, 24, s2
	v_mov_b32_e32 v126, v123
	v_or_b32_e32 v132, s92, v131
	v_add_f32_e32 v122, 1.0, v122
	v_rcp_f32_e32 v122, v122
	v_ashrrev_i32_e32 v133, 31, v132
	v_fmamk_f32 v130, v130, 0x3a000000, v1
	v_rsq_f32_e32 v130, v130
	v_mul_f32_e32 v122, v169, v122
	v_mul_f32_e32 v131, v168, v122
	v_pk_mul_f32 v[122:123], v[126:127], v[166:167] op_sel_hi:[1,0]
	s_nop 0
	v_mul_f32_e32 v126, 0xbfb8aa3b, v123
	v_min_f32_e32 v126, 0x42a00000, v126
	v_exp_f32_e32 v126, v126
	s_nop 0
	v_add_f32_e32 v126, 1.0, v126
	v_rcp_f32_e32 v126, v126
	s_nop 0
	v_mul_f32_e32 v123, v123, v126
	v_mul_f32_e32 v126, v122, v123
	v_mov_b32_e32 v122, v124
	v_mov_b32_e32 v123, v128
	v_pk_mul_f32 v[122:123], v[122:123], v[166:167] op_sel_hi:[1,0]
	v_mov_b32_e32 v128, v125
	v_mul_f32_e32 v124, 0xbfb8aa3b, v123
	v_min_f32_e32 v124, 0x42a00000, v124
; __device__ __forceinline__ unsigned cvt_pk_bf16(float lo, float hi) { unsigned r; asm volatile("v_cvt_pk_bf16_f32 %0, %1, %2" : "=v"(r) : "v"(lo), "v"(hi)); return r; }
; __device__ __forceinline__ float expneg(float g) { return ex2(fminf(-g * 1.4426950408889634f, 80.f)); }
; __device__ __forceinline__ u32x4 pack8(const f32x4& a, const f32x4& b) { u32x4 w; w.x = cvt_pk_bf16(a[0], a[1]); w.y = cvt_pk_bf16(a[2], a[3]); w.z = cvt_pk_bf16(b[0], b[1]); w.w = cvt_pk_bf16(b[2], b[3]); return w; }
;     __device__ __forceinline__ void operator()(const f32x4 (&acc)[2][2][4][2], const Unit& u, int wr, int wc, int fr, int fq) const {
;     ...
;         for (int ai = 0; ai < 2; ++ai)
; #pragma unroll
;             for (int m = 0; m < 4; ++m) { f32x4 v[2]; const float rs = rsv[ai][m];
; #pragma unroll
;                 for (int n = 0; n < 2; ++n)
; #pragma unroll
;                     for (int i = 0; i < 4; ++i) { const float g = acc[ai][0][m][n][i] * rs; v[n][i] = g * __builtin_amdgcn_rcpf(1.f + expneg(g)) * (acc[ai][1][m][n][i] * rs); }
;                 *(u32x4*)(act + (size_t)(rowt + ai * HALF + m * 16) * 5632 + col0) = pack8(v[0], v[1]); }
	v_exp_f32_e32 v124, v124
	s_nop 0
	v_add_f32_e32 v124, 1.0, v124
	v_rcp_f32_e32 v124, v124
	s_nop 0
	v_mul_f32_e32 v123, v123, v124
	v_mul_f32_e32 v124, v122, v123
	v_pk_mul_f32 v[122:123], v[128:129], v[166:167] op_sel_hi:[1,0]
	s_nop 0
	v_mul_f32_e32 v125, 0xbfb8aa3b, v123
	v_min_f32_e32 v125, 0x42a00000, v125
	v_exp_f32_e32 v125, v125
	s_nop 0
	v_add_f32_e32 v125, 1.0, v125
	v_rcp_f32_e32 v125, v125
	s_nop 0
	v_mul_f32_e32 v123, v123, v125
	v_mul_f32_e32 v125, v122, v123
	v_mov_b32_e32 v122, v114
	v_mov_b32_e32 v123, v118
	v_pk_mul_f32 v[122:123], v[122:123], v[166:167] op_sel_hi:[1,0]
	v_mov_b32_e32 v118, v115
	v_mul_f32_e32 v114, 0xbfb8aa3b, v123
	v_min_f32_e32 v114, 0x42a00000, v114
	v_exp_f32_e32 v114, v114
	s_nop 0
	v_add_f32_e32 v114, 1.0, v114
	v_rcp_f32_e32 v114, v114
	s_nop 0
	v_mul_f32_e32 v114, v123, v114
	v_mul_f32_e32 v122, v122, v114
	v_pk_mul_f32 v[114:115], v[118:119], v[166:167] op_sel_hi:[1,0]
	s_nop 0
	v_mul_f32_e32 v118, 0xbfb8aa3b, v115
	v_min_f32_e32 v118, 0x42a00000, v118
	v_exp_f32_e32 v118, v118
	s_nop 0
	v_add_f32_e32 v118, 1.0, v118
	v_rcp_f32_e32 v118, v118
	s_nop 0
	v_mul_f32_e32 v115, v115, v118
	v_mul_f32_e32 v123, v114, v115
	v_mov_b32_e32 v114, v116
	v_mov_b32_e32 v115, v120
	v_pk_mul_f32 v[114:115], v[114:115], v[166:167] op_sel_hi:[1,0]
	v_mov_b32_e32 v120, v117
	v_mul_f32_e32 v116, 0xbfb8aa3b, v115
	v_min_f32_e32 v116, 0x42a00000, v116
	v_exp_f32_e32 v116, v116
	v_cvt_pk_bf16_f32 v118, v131, v126
	v_cvt_pk_bf16_f32 v119, v124, v125
	s_nop 0
	v_add_f32_e32 v116, 1.0, v116
	v_rcp_f32_e32 v116, v116
	s_nop 0
	v_mul_f32_e32 v115, v115, v116
	v_mul_f32_e32 v116, v114, v115
	v_pk_mul_f32 v[114:115], v[120:121], v[166:167] op_sel_hi:[1,0]
	v_cvt_pk_bf16_f32 v120, v122, v123
	s_nop 0
	v_mul_f32_e32 v117, 0xbfb8aa3b, v115
	v_min_f32_e32 v117, 0x42a00000, v117
	v_exp_f32_e32 v117, v117
	s_nop 0
	v_add_f32_e32 v117, 1.0, v117
	v_rcp_f32_e32 v117, v117
	s_nop 0
	v_mul_f32_e32 v115, v115, v117
	v_mul_f32_e32 v114, v114, v115
	v_cvt_pk_bf16_f32 v121, v116, v114
	v_mov_b64_e32 v[114:115], s[18:19]
	v_mad_i64_i32 v[122:123], s[2:3], v164, s49, v[114:115]
	v_lshlrev_b64 v[116:117], 1, v[132:133]
	v_lshl_add_u64 v[122:123], v[122:123], 0, v[116:117]
	global_store_dwordx4 v[122:123], v[118:121], off
	s_nop 1
	v_mov_b32_e32 v118, v106
	v_mov_b32_e32 v119, v110
	v_pk_mul_f32 v[118:119], v[118:119], v[162:163] op_sel_hi:[1,0]
	v_mov_b32_e32 v110, v107
	v_mul_f32_e32 v106, 0xbfb8aa3b, v119
	v_min_f32_e32 v106, 0x42a00000, v106
	v_exp_f32_e32 v106, v106
	s_nop 0
	v_add_f32_e32 v106, 1.0, v106
	v_rcp_f32_e32 v106, v106
	s_nop 0
	v_mul_f32_e32 v106, v119, v106
	v_mul_f32_e32 v118, v118, v106
	v_pk_mul_f32 v[106:107], v[110:111], v[162:163] op_sel_hi:[1,0]
	s_nop 0
	v_mul_f32_e32 v110, 0xbfb8aa3b, v107
	v_min_f32_e32 v110, 0x42a00000, v110
	v_exp_f32_e32 v110, v110
	s_nop 0
	v_add_f32_e32 v110, 1.0, v110
	v_rcp_f32_e32 v110, v110
	s_nop 0
	v_mul_f32_e32 v107, v107, v110
	v_mul_f32_e32 v110, v106, v107
	v_mov_b32_e32 v106, v108
	v_mov_b32_e32 v107, v112
	v_pk_mul_f32 v[106:107], v[106:107], v[162:163] op_sel_hi:[1,0]
	v_mov_b32_e32 v112, v109
	v_mul_f32_e32 v108, 0xbfb8aa3b, v107
	v_min_f32_e32 v108, 0x42a00000, v108
	v_exp_f32_e32 v108, v108
	s_nop 0
	v_add_f32_e32 v108, 1.0, v108
	v_rcp_f32_e32 v108, v108
	s_nop 0
	v_mul_f32_e32 v107, v107, v108
	v_mul_f32_e32 v108, v106, v107
	v_pk_mul_f32 v[106:107], v[112:113], v[162:163] op_sel_hi:[1,0]
	s_nop 0
	v_mul_f32_e32 v109, 0xbfb8aa3b, v107
	v_min_f32_e32 v109, 0x42a00000, v109
	v_exp_f32_e32 v109, v109
	s_nop 0
	v_add_f32_e32 v109, 1.0, v109
	v_rcp_f32_e32 v109, v109
	s_nop 0
	v_mul_f32_e32 v107, v107, v109
	v_mul_f32_e32 v109, v106, v107
	v_mov_b32_e32 v106, v98
	v_mov_b32_e32 v107, v102
	v_pk_mul_f32 v[106:107], v[106:107], v[162:163] op_sel_hi:[1,0]
	v_mov_b32_e32 v102, v99
	v_mul_f32_e32 v98, 0xbfb8aa3b, v107
	v_min_f32_e32 v98, 0x42a00000, v98
	v_exp_f32_e32 v98, v98
	s_nop 0
	v_add_f32_e32 v98, 1.0, v98
	v_rcp_f32_e32 v98, v98
	s_nop 0
	v_mul_f32_e32 v98, v107, v98
	v_mul_f32_e32 v106, v106, v98
	v_pk_mul_f32 v[98:99], v[102:103], v[162:163] op_sel_hi:[1,0]
	s_nop 0
	v_mul_f32_e32 v102, 0xbfb8aa3b, v99
	v_min_f32_e32 v102, 0x42a00000, v102
	v_exp_f32_e32 v102, v102
	s_nop 0
	v_add_f32_e32 v102, 1.0, v102
	v_rcp_f32_e32 v102, v102
	s_nop 0
	v_mul_f32_e32 v99, v99, v102
	v_mul_f32_e32 v102, v98, v99
	v_mov_b32_e32 v98, v100
	v_mov_b32_e32 v99, v104
	v_pk_mul_f32 v[98:99], v[98:99], v[162:163] op_sel_hi:[1,0]
	v_mov_b32_e32 v104, v101
	v_mul_f32_e32 v100, 0xbfb8aa3b, v99
	v_min_f32_e32 v100, 0x42a00000, v100
	v_exp_f32_e32 v100, v100
	s_nop 0
	v_add_f32_e32 v100, 1.0, v100
	v_rcp_f32_e32 v100, v100
	s_nop 0
	v_mul_f32_e32 v99, v99, v100
	v_mul_f32_e32 v103, v98, v99
	v_pk_mul_f32 v[98:99], v[104:105], v[162:163] op_sel_hi:[1,0]
	s_nop 0
	v_mul_f32_e32 v100, 0xbfb8aa3b, v99
	v_min_f32_e32 v100, 0x42a00000, v100
	v_exp_f32_e32 v100, v100
	s_nop 0
	v_add_f32_e32 v100, 1.0, v100
	v_rcp_f32_e32 v100, v100
	s_nop 0
	v_mul_f32_e32 v99, v99, v100
	v_mul_f32_e32 v101, v98, v99
	v_cvt_pk_bf16_f32 v98, v118, v110
	v_cvt_pk_bf16_f32 v99, v108, v109
	v_cvt_pk_bf16_f32 v100, v106, v102
	v_cvt_pk_bf16_f32 v101, v103, v101
	v_mad_i64_i32 v[102:103], s[2:3], v160, s49, v[114:115]
	v_lshl_add_u64 v[102:103], v[102:103], 0, v[116:117]
	global_store_dwordx4 v[102:103], v[98:101], off
	s_nop 1
	v_mov_b32_e32 v98, v90
	v_mov_b32_e32 v99, v94
	v_pk_mul_f32 v[98:99], v[98:99], v[158:159] op_sel_hi:[1,0]
	v_mov_b32_e32 v94, v91
	v_mul_f32_e32 v90, 0xbfb8aa3b, v99
	v_min_f32_e32 v90, 0x42a00000, v90
	v_exp_f32_e32 v90, v90
	s_nop 0
	v_add_f32_e32 v90, 1.0, v90
	v_rcp_f32_e32 v90, v90
	s_nop 0
; __device__ __forceinline__ unsigned cvt_pk_bf16(float lo, float hi) { unsigned r; asm volatile("v_cvt_pk_bf16_f32 %0, %1, %2" : "=v"(r) : "v"(lo), "v"(hi)); return r; }
; __device__ __forceinline__ float expneg(float g) { return ex2(fminf(-g * 1.4426950408889634f, 80.f)); }
; __device__ __forceinline__ u32x4 pack8(const f32x4& a, const f32x4& b) { u32x4 w; w.x = cvt_pk_bf16(a[0], a[1]); w.y = cvt_pk_bf16(a[2], a[3]); w.z = cvt_pk_bf16(b[0], b[1]); w.w = cvt_pk_bf16(b[2], b[3]); return w; }
;     __device__ __forceinline__ void operator()(const f32x4 (&acc)[2][2][4][2], const Unit& u, int wr, int wc, int fr, int fq) const {
;     ...
;         for (int ai = 0; ai < 2; ++ai)
; #pragma unroll
;             for (int m = 0; m < 4; ++m) { f32x4 v[2]; const float rs = rsv[ai][m];
; #pragma unroll
;                 for (int n = 0; n < 2; ++n)
; #pragma unroll
;                     for (int i = 0; i < 4; ++i) { const float g = acc[ai][0][m][n][i] * rs; v[n][i] = g * __builtin_amdgcn_rcpf(1.f + expneg(g)) * (acc[ai][1][m][n][i] * rs); }
;                 *(u32x4*)(act + (size_t)(rowt + ai * HALF + m * 16) * 5632 + col0) = pack8(v[0], v[1]); }
	v_mul_f32_e32 v90, v99, v90
	v_mul_f32_e32 v98, v98, v90
	v_pk_mul_f32 v[90:91], v[94:95], v[158:159] op_sel_hi:[1,0]
	s_nop 0
	v_mul_f32_e32 v94, 0xbfb8aa3b, v91
	v_min_f32_e32 v94, 0x42a00000, v94
	v_exp_f32_e32 v94, v94
	s_nop 0
	v_add_f32_e32 v94, 1.0, v94
	v_rcp_f32_e32 v94, v94
	s_nop 0
	v_mul_f32_e32 v91, v91, v94
	v_mul_f32_e32 v94, v90, v91
	v_mov_b32_e32 v90, v92
	v_mov_b32_e32 v91, v96
	v_pk_mul_f32 v[90:91], v[90:91], v[158:159] op_sel_hi:[1,0]
	v_mov_b32_e32 v96, v93
	v_mul_f32_e32 v92, 0xbfb8aa3b, v91
	v_min_f32_e32 v92, 0x42a00000, v92
	v_exp_f32_e32 v92, v92
	s_nop 0
	v_add_f32_e32 v92, 1.0, v92
	v_rcp_f32_e32 v92, v92
	s_nop 0
	v_mul_f32_e32 v91, v91, v92
	v_mul_f32_e32 v92, v90, v91
	v_pk_mul_f32 v[90:91], v[96:97], v[158:159] op_sel_hi:[1,0]
	s_nop 0
	v_mul_f32_e32 v93, 0xbfb8aa3b, v91
	v_min_f32_e32 v93, 0x42a00000, v93
	v_exp_f32_e32 v93, v93
	s_nop 0
	v_add_f32_e32 v93, 1.0, v93
	v_rcp_f32_e32 v93, v93
	s_nop 0
	v_mul_f32_e32 v91, v91, v93
	v_mul_f32_e32 v93, v90, v91
	v_mov_b32_e32 v90, v82
	v_mov_b32_e32 v91, v86
	v_pk_mul_f32 v[90:91], v[90:91], v[158:159] op_sel_hi:[1,0]
	v_mov_b32_e32 v86, v83
	v_mul_f32_e32 v82, 0xbfb8aa3b, v91
	v_min_f32_e32 v82, 0x42a00000, v82
	v_exp_f32_e32 v82, v82
	s_nop 0
	v_add_f32_e32 v82, 1.0, v82
	v_rcp_f32_e32 v82, v82
	s_nop 0
	v_mul_f32_e32 v82, v91, v82
	v_mul_f32_e32 v90, v90, v82
	v_pk_mul_f32 v[82:83], v[86:87], v[158:159] op_sel_hi:[1,0]
	s_nop 0
	v_mul_f32_e32 v86, 0xbfb8aa3b, v83
	v_min_f32_e32 v86, 0x42a00000, v86
	v_exp_f32_e32 v86, v86
	s_nop 0
	v_add_f32_e32 v86, 1.0, v86
	v_rcp_f32_e32 v86, v86
	s_nop 0
	v_mul_f32_e32 v83, v83, v86
	v_mul_f32_e32 v86, v82, v83
	v_mov_b32_e32 v82, v84
	v_mov_b32_e32 v83, v88
	v_pk_mul_f32 v[82:83], v[82:83], v[158:159] op_sel_hi:[1,0]
	v_mov_b32_e32 v88, v85
	v_mul_f32_e32 v84, 0xbfb8aa3b, v83
	v_min_f32_e32 v84, 0x42a00000, v84
	v_exp_f32_e32 v84, v84
	s_nop 0
	v_add_f32_e32 v84, 1.0, v84
	v_rcp_f32_e32 v84, v84
	s_nop 0
	v_mul_f32_e32 v83, v83, v84
	v_mul_f32_e32 v87, v82, v83
	v_pk_mul_f32 v[82:83], v[88:89], v[158:159] op_sel_hi:[1,0]
	s_nop 0
	v_mul_f32_e32 v84, 0xbfb8aa3b, v83
	v_min_f32_e32 v84, 0x42a00000, v84
	v_exp_f32_e32 v84, v84
	s_nop 0
	v_add_f32_e32 v84, 1.0, v84
	v_rcp_f32_e32 v84, v84
	s_nop 0
	v_mul_f32_e32 v83, v83, v84
	v_mul_f32_e32 v85, v82, v83
	v_cvt_pk_bf16_f32 v82, v98, v94
	v_cvt_pk_bf16_f32 v83, v92, v93
	v_cvt_pk_bf16_f32 v84, v90, v86
	v_cvt_pk_bf16_f32 v85, v87, v85
	v_mad_i64_i32 v[86:87], s[2:3], v156, s49, v[114:115]
	v_lshl_add_u64 v[86:87], v[86:87], 0, v[116:117]
	global_store_dwordx4 v[86:87], v[82:85], off
	s_nop 1
	v_mov_b32_e32 v82, v74
	v_mov_b32_e32 v83, v78
	v_pk_mul_f32 v[82:83], v[82:83], v[154:155] op_sel_hi:[1,0]
	v_mov_b32_e32 v78, v75
	v_mul_f32_e32 v74, 0xbfb8aa3b, v83
	v_min_f32_e32 v74, 0x42a00000, v74
	v_exp_f32_e32 v74, v74
	s_nop 0
	v_add_f32_e32 v74, 1.0, v74
	v_rcp_f32_e32 v74, v74
	s_nop 0
	v_mul_f32_e32 v74, v83, v74
	v_mul_f32_e32 v82, v82, v74
	v_pk_mul_f32 v[74:75], v[78:79], v[154:155] op_sel_hi:[1,0]
	s_nop 0
	v_mul_f32_e32 v78, 0xbfb8aa3b, v75
	v_min_f32_e32 v78, 0x42a00000, v78
	v_exp_f32_e32 v78, v78
	s_nop 0
	v_add_f32_e32 v78, 1.0, v78
	v_rcp_f32_e32 v78, v78
	s_nop 0
	v_mul_f32_e32 v75, v75, v78
	v_mul_f32_e32 v78, v74, v75
	v_mov_b32_e32 v74, v76
	v_mov_b32_e32 v75, v80
	v_pk_mul_f32 v[74:75], v[74:75], v[154:155] op_sel_hi:[1,0]
	v_mov_b32_e32 v80, v77
	v_mul_f32_e32 v76, 0xbfb8aa3b, v75
	v_min_f32_e32 v76, 0x42a00000, v76
	v_exp_f32_e32 v76, v76
	s_nop 0
	v_add_f32_e32 v76, 1.0, v76
	v_rcp_f32_e32 v76, v76
	s_nop 0
	v_mul_f32_e32 v75, v75, v76
	v_mul_f32_e32 v76, v74, v75
	v_pk_mul_f32 v[74:75], v[80:81], v[154:155] op_sel_hi:[1,0]
	s_nop 0
	v_mul_f32_e32 v77, 0xbfb8aa3b, v75
	v_min_f32_e32 v77, 0x42a00000, v77
	v_exp_f32_e32 v77, v77
	s_nop 0
	v_add_f32_e32 v77, 1.0, v77
	v_rcp_f32_e32 v77, v77
	s_nop 0
	v_mul_f32_e32 v75, v75, v77
	v_mul_f32_e32 v77, v74, v75
	v_mov_b32_e32 v74, v66
	v_mov_b32_e32 v75, v70
	v_pk_mul_f32 v[74:75], v[74:75], v[154:155] op_sel_hi:[1,0]
	v_mov_b32_e32 v70, v67
	v_mul_f32_e32 v66, 0xbfb8aa3b, v75
	v_min_f32_e32 v66, 0x42a00000, v66
	v_exp_f32_e32 v66, v66
	s_nop 0
	v_add_f32_e32 v66, 1.0, v66
	v_rcp_f32_e32 v66, v66
	s_nop 0
	v_mul_f32_e32 v66, v75, v66
	v_mul_f32_e32 v74, v74, v66
	v_pk_mul_f32 v[66:67], v[70:71], v[154:155] op_sel_hi:[1,0]
	s_nop 0
	v_mul_f32_e32 v70, 0xbfb8aa3b, v67
	v_min_f32_e32 v70, 0x42a00000, v70
	v_exp_f32_e32 v70, v70
	s_nop 0
	v_add_f32_e32 v70, 1.0, v70
	v_rcp_f32_e32 v70, v70
	s_nop 0
	v_mul_f32_e32 v67, v67, v70
	v_mul_f32_e32 v70, v66, v67
	v_mov_b32_e32 v66, v68
	v_mov_b32_e32 v67, v72
	v_pk_mul_f32 v[66:67], v[66:67], v[154:155] op_sel_hi:[1,0]
	v_mov_b32_e32 v72, v69
	v_mul_f32_e32 v68, 0xbfb8aa3b, v67
	v_min_f32_e32 v68, 0x42a00000, v68
	v_exp_f32_e32 v68, v68
	s_nop 0
	v_add_f32_e32 v68, 1.0, v68
	v_rcp_f32_e32 v68, v68
	s_nop 0
	v_mul_f32_e32 v67, v67, v68
	v_mul_f32_e32 v71, v66, v67
	v_pk_mul_f32 v[66:67], v[72:73], v[154:155] op_sel_hi:[1,0]
	s_nop 0
	v_mul_f32_e32 v68, 0xbfb8aa3b, v67
	v_min_f32_e32 v68, 0x42a00000, v68
	v_exp_f32_e32 v68, v68
	s_nop 0
	v_add_f32_e32 v68, 1.0, v68
	v_rcp_f32_e32 v68, v68
	s_nop 0
	v_mul_f32_e32 v67, v67, v68
	v_mul_f32_e32 v69, v66, v67
	v_cvt_pk_bf16_f32 v66, v82, v78
	v_cvt_pk_bf16_f32 v67, v76, v77
	v_cvt_pk_bf16_f32 v68, v74, v70
	v_cvt_pk_bf16_f32 v69, v71, v69
	v_mad_i64_i32 v[70:71], s[2:3], v152, s49, v[114:115]
	v_lshl_add_u64 v[70:71], v[70:71], 0, v[116:117]
	global_store_dwordx4 v[70:71], v[66:69], off
	s_nop 1
	v_mov_b32_e32 v66, v58
	v_mov_b32_e32 v67, v62
	v_pk_mul_f32 v[66:67], v[66:67], v[150:151] op_sel_hi:[1,0]
	v_mov_b32_e32 v62, v59
; __device__ __forceinline__ unsigned cvt_pk_bf16(float lo, float hi) { unsigned r; asm volatile("v_cvt_pk_bf16_f32 %0, %1, %2" : "=v"(r) : "v"(lo), "v"(hi)); return r; }
; __device__ __forceinline__ float expneg(float g) { return ex2(fminf(-g * 1.4426950408889634f, 80.f)); }
; __device__ __forceinline__ u32x4 pack8(const f32x4& a, const f32x4& b) { u32x4 w; w.x = cvt_pk_bf16(a[0], a[1]); w.y = cvt_pk_bf16(a[2], a[3]); w.z = cvt_pk_bf16(b[0], b[1]); w.w = cvt_pk_bf16(b[2], b[3]); return w; }
;     __device__ __forceinline__ void operator()(const f32x4 (&acc)[2][2][4][2], const Unit& u, int wr, int wc, int fr, int fq) const {
;     ...
;         for (int ai = 0; ai < 2; ++ai)
; #pragma unroll
;             for (int m = 0; m < 4; ++m) { f32x4 v[2]; const float rs = rsv[ai][m];
; #pragma unroll
;                 for (int n = 0; n < 2; ++n)
; #pragma unroll
;                     for (int i = 0; i < 4; ++i) { const float g = acc[ai][0][m][n][i] * rs; v[n][i] = g * __builtin_amdgcn_rcpf(1.f + expneg(g)) * (acc[ai][1][m][n][i] * rs); }
;                 *(u32x4*)(act + (size_t)(rowt + ai * HALF + m * 16) * 5632 + col0) = pack8(v[0], v[1]); }
	v_mul_f32_e32 v58, 0xbfb8aa3b, v67
	v_min_f32_e32 v58, 0x42a00000, v58
	v_exp_f32_e32 v58, v58
	s_nop 0
	v_add_f32_e32 v58, 1.0, v58
	v_rcp_f32_e32 v58, v58
	s_nop 0
	v_mul_f32_e32 v58, v67, v58
	v_mul_f32_e32 v66, v66, v58
	v_pk_mul_f32 v[58:59], v[62:63], v[150:151] op_sel_hi:[1,0]
	s_nop 0
	v_mul_f32_e32 v62, 0xbfb8aa3b, v59
	v_min_f32_e32 v62, 0x42a00000, v62
	v_exp_f32_e32 v62, v62
	s_nop 0
	v_add_f32_e32 v62, 1.0, v62
	v_rcp_f32_e32 v62, v62
	s_nop 0
	v_mul_f32_e32 v59, v59, v62
	v_mul_f32_e32 v62, v58, v59
	v_mov_b32_e32 v58, v60
	v_mov_b32_e32 v59, v64
	v_pk_mul_f32 v[58:59], v[58:59], v[150:151] op_sel_hi:[1,0]
	v_mov_b32_e32 v64, v61
	v_mul_f32_e32 v60, 0xbfb8aa3b, v59
	v_min_f32_e32 v60, 0x42a00000, v60
	v_exp_f32_e32 v60, v60
	s_nop 0
	v_add_f32_e32 v60, 1.0, v60
	v_rcp_f32_e32 v60, v60
	s_nop 0
	v_mul_f32_e32 v59, v59, v60
	v_mul_f32_e32 v60, v58, v59
	v_pk_mul_f32 v[58:59], v[64:65], v[150:151] op_sel_hi:[1,0]
	s_nop 0
	v_mul_f32_e32 v61, 0xbfb8aa3b, v59
	v_min_f32_e32 v61, 0x42a00000, v61
	v_exp_f32_e32 v61, v61
	s_nop 0
	v_add_f32_e32 v61, 1.0, v61
	v_rcp_f32_e32 v61, v61
	s_nop 0
	v_mul_f32_e32 v59, v59, v61
	v_mul_f32_e32 v61, v58, v59
	v_mov_b32_e32 v58, v50
	v_mov_b32_e32 v59, v54
	v_pk_mul_f32 v[58:59], v[58:59], v[150:151] op_sel_hi:[1,0]
	v_mov_b32_e32 v54, v51
	v_mul_f32_e32 v50, 0xbfb8aa3b, v59
	v_min_f32_e32 v50, 0x42a00000, v50
	v_exp_f32_e32 v50, v50
	s_nop 0
	v_add_f32_e32 v50, 1.0, v50
	v_rcp_f32_e32 v50, v50
	s_nop 0
	v_mul_f32_e32 v50, v59, v50
	v_mul_f32_e32 v58, v58, v50
	v_pk_mul_f32 v[50:51], v[54:55], v[150:151] op_sel_hi:[1,0]
	s_nop 0
	v_mul_f32_e32 v54, 0xbfb8aa3b, v51
	v_min_f32_e32 v54, 0x42a00000, v54
	v_exp_f32_e32 v54, v54
	s_nop 0
	v_add_f32_e32 v54, 1.0, v54
	v_rcp_f32_e32 v54, v54
	s_nop 0
	v_mul_f32_e32 v51, v51, v54
	v_mul_f32_e32 v54, v50, v51
	v_mov_b32_e32 v50, v52
	v_mov_b32_e32 v51, v56
	v_pk_mul_f32 v[50:51], v[50:51], v[150:151] op_sel_hi:[1,0]
	v_mov_b32_e32 v56, v53
	v_mul_f32_e32 v52, 0xbfb8aa3b, v51
	v_min_f32_e32 v52, 0x42a00000, v52
	v_exp_f32_e32 v52, v52
	s_nop 0
	v_add_f32_e32 v52, 1.0, v52
	v_rcp_f32_e32 v52, v52
	s_nop 0
	v_mul_f32_e32 v51, v51, v52
	v_mul_f32_e32 v55, v50, v51
	v_pk_mul_f32 v[50:51], v[56:57], v[150:151] op_sel_hi:[1,0]
	s_nop 0
	v_mul_f32_e32 v52, 0xbfb8aa3b, v51
	v_min_f32_e32 v52, 0x42a00000, v52
	v_exp_f32_e32 v52, v52
	s_nop 0
	v_add_f32_e32 v52, 1.0, v52
	v_rcp_f32_e32 v52, v52
	s_nop 0
	v_mul_f32_e32 v51, v51, v52
	v_mul_f32_e32 v53, v50, v51
	v_cvt_pk_bf16_f32 v50, v66, v62
	v_cvt_pk_bf16_f32 v51, v60, v61
	v_cvt_pk_bf16_f32 v52, v58, v54
	v_cvt_pk_bf16_f32 v53, v55, v53
	v_mad_i64_i32 v[54:55], s[2:3], v148, s49, v[114:115]
	v_lshl_add_u64 v[54:55], v[54:55], 0, v[116:117]
	global_store_dwordx4 v[54:55], v[50:53], off
	s_nop 1
	v_mov_b32_e32 v50, v42
	v_mov_b32_e32 v51, v46
	v_pk_mul_f32 v[50:51], v[50:51], v[146:147] op_sel_hi:[1,0]
	v_mov_b32_e32 v46, v43
	v_mul_f32_e32 v42, 0xbfb8aa3b, v51
	v_min_f32_e32 v42, 0x42a00000, v42
	v_exp_f32_e32 v42, v42
	s_nop 0
	v_add_f32_e32 v42, 1.0, v42
	v_rcp_f32_e32 v42, v42
	s_nop 0
	v_mul_f32_e32 v42, v51, v42
	v_mul_f32_e32 v50, v50, v42
	v_pk_mul_f32 v[42:43], v[46:47], v[146:147] op_sel_hi:[1,0]
	s_nop 0
	v_mul_f32_e32 v46, 0xbfb8aa3b, v43
	v_min_f32_e32 v46, 0x42a00000, v46
	v_exp_f32_e32 v46, v46
	s_nop 0
	v_add_f32_e32 v46, 1.0, v46
	v_rcp_f32_e32 v46, v46
	s_nop 0
	v_mul_f32_e32 v43, v43, v46
	v_mul_f32_e32 v46, v42, v43
	v_mov_b32_e32 v42, v44
	v_mov_b32_e32 v43, v48
	v_pk_mul_f32 v[42:43], v[42:43], v[146:147] op_sel_hi:[1,0]
	v_mov_b32_e32 v48, v45
	v_mul_f32_e32 v44, 0xbfb8aa3b, v43
	v_min_f32_e32 v44, 0x42a00000, v44
	v_exp_f32_e32 v44, v44
	s_nop 0
	v_add_f32_e32 v44, 1.0, v44
	v_rcp_f32_e32 v44, v44
	s_nop 0
	v_mul_f32_e32 v43, v43, v44
	v_mul_f32_e32 v44, v42, v43
	v_pk_mul_f32 v[42:43], v[48:49], v[146:147] op_sel_hi:[1,0]
	s_nop 0
	v_mul_f32_e32 v45, 0xbfb8aa3b, v43
	v_min_f32_e32 v45, 0x42a00000, v45
	v_exp_f32_e32 v45, v45
	s_nop 0
	v_add_f32_e32 v45, 1.0, v45
	v_rcp_f32_e32 v45, v45
	s_nop 0
	v_mul_f32_e32 v43, v43, v45
	v_mul_f32_e32 v45, v42, v43
	v_mov_b32_e32 v42, v34
	v_mov_b32_e32 v43, v38
	v_pk_mul_f32 v[42:43], v[42:43], v[146:147] op_sel_hi:[1,0]
	v_mov_b32_e32 v38, v35
	v_mul_f32_e32 v34, 0xbfb8aa3b, v43
	v_min_f32_e32 v34, 0x42a00000, v34
	v_exp_f32_e32 v34, v34
	s_nop 0
	v_add_f32_e32 v34, 1.0, v34
	v_rcp_f32_e32 v34, v34
	s_nop 0
	v_mul_f32_e32 v34, v43, v34
	v_mul_f32_e32 v42, v42, v34
	v_pk_mul_f32 v[34:35], v[38:39], v[146:147] op_sel_hi:[1,0]
	s_nop 0
	v_mul_f32_e32 v38, 0xbfb8aa3b, v35
	v_min_f32_e32 v38, 0x42a00000, v38
	v_exp_f32_e32 v38, v38
	s_nop 0
	v_add_f32_e32 v38, 1.0, v38
	v_rcp_f32_e32 v38, v38
	s_nop 0
	v_mul_f32_e32 v35, v35, v38
	v_mul_f32_e32 v38, v34, v35
	v_mov_b32_e32 v34, v36
	v_mov_b32_e32 v35, v40
	v_pk_mul_f32 v[34:35], v[34:35], v[146:147] op_sel_hi:[1,0]
	v_mov_b32_e32 v40, v37
	v_mul_f32_e32 v36, 0xbfb8aa3b, v35
	v_min_f32_e32 v36, 0x42a00000, v36
	v_exp_f32_e32 v36, v36
	s_nop 0
	v_add_f32_e32 v36, 1.0, v36
	v_rcp_f32_e32 v36, v36
	s_nop 0
	v_mul_f32_e32 v35, v35, v36
	v_mul_f32_e32 v39, v34, v35
	v_pk_mul_f32 v[34:35], v[40:41], v[146:147] op_sel_hi:[1,0]
	s_nop 0
	v_mul_f32_e32 v36, 0xbfb8aa3b, v35
	v_min_f32_e32 v36, 0x42a00000, v36
	v_exp_f32_e32 v36, v36
	s_nop 0
	v_add_f32_e32 v36, 1.0, v36
	v_rcp_f32_e32 v36, v36
	s_nop 0
	v_mul_f32_e32 v35, v35, v36
	v_mul_f32_e32 v37, v34, v35
	v_cvt_pk_bf16_f32 v34, v50, v46
	v_cvt_pk_bf16_f32 v35, v44, v45
	v_cvt_pk_bf16_f32 v36, v42, v38
	v_cvt_pk_bf16_f32 v37, v39, v37
	v_mad_i64_i32 v[38:39], s[2:3], v144, s49, v[114:115]
	v_lshl_add_u64 v[38:39], v[38:39], 0, v[116:117]
; __device__ __forceinline__ u32x4 pack8(const f32x4& a, const f32x4& b) { u32x4 w; w.x = cvt_pk_bf16(a[0], a[1]); w.y = cvt_pk_bf16(a[2], a[3]); w.z = cvt_pk_bf16(b[0], b[1]); w.w = cvt_pk_bf16(b[2], b[3]); return w; }
; __device__ __forceinline__ float expneg(float g) { return ex2(fminf(-g * 1.4426950408889634f, 80.f)); }
; #define PG8_BAR __builtin_amdgcn_s_barrier()
;     __device__ __forceinline__ void operator()(const f32x4 (&acc)[2][2][4][2], const Unit& u, int wr, int wc, int fr, int fq) const {
;     ...
;         for (int ai = 0; ai < 2; ++ai)
; #pragma unroll
;             for (int m = 0; m < 4; ++m) { f32x4 v[2]; const float rs = rsv[ai][m];
; #pragma unroll
;                 for (int n = 0; n < 2; ++n)
; #pragma unroll
;                     for (int i = 0; i < 4; ++i) { const float g = acc[ai][0][m][n][i] * rs; v[n][i] = g * __builtin_amdgcn_rcpf(1.f + expneg(g)) * (acc[ai][1][m][n][i] * rs); }
;                 *(u32x4*)(act + (size_t)(rowt + ai * HALF + m * 16) * 5632 + col0) = pack8(v[0], v[1]); }
; template <class Epi, class Sched, bool ALIGN_EPI = false, bool SP2 = false, bool SLIVER = false>
; __device__ __forceinline__ void gemm_phase(PG8_LAS unsigned char* lds, const Gemm g, const Sched& S, const Epi& E) {
;     ...
;         if (!has_next) break;
;         if (fin) {
; #pragma unroll
;         for (int a = 0; a < 2; ++a)
; #pragma unroll
;             for (int b = 0; b < 2; ++b)
; #pragma unroll
;                 for (int m = 0; m < 4; ++m)
; #pragma unroll
;                     for (int n = 0; n < 2; ++n) acc[a][b][m][n] = (f32x4){0.f, 0.f, 0.f, 0.f};
;         accs[0] = (f32x4){0.f, 0.f, 0.f, 0.f}; accs[1] = (f32x4){0.f, 0.f, 0.f, 0.f};
;         }
;         cur = nxt; cA = nA; cB = nB; cS = nS; nt = Epi::nt(cur.seg, K); ++ui;
;         if constexpr (ALIGN_EPI) { if (wr == 1) PG8_BAR; }
	global_store_dwordx4 v[38:39], v[34:37], off
	s_nop 1
	v_mov_b32_e32 v34, v26
	v_mov_b32_e32 v35, v30
	v_pk_mul_f32 v[34:35], v[34:35], v[142:143] op_sel_hi:[1,0]
	v_mov_b32_e32 v30, v27
	v_mul_f32_e32 v26, 0xbfb8aa3b, v35
	v_min_f32_e32 v26, 0x42a00000, v26
	v_exp_f32_e32 v26, v26
	s_nop 0
	v_add_f32_e32 v26, 1.0, v26
	v_rcp_f32_e32 v26, v26
	s_nop 0
	v_mul_f32_e32 v26, v35, v26
	v_mul_f32_e32 v34, v34, v26
	v_pk_mul_f32 v[26:27], v[30:31], v[142:143] op_sel_hi:[1,0]
	s_nop 0
	v_mul_f32_e32 v30, 0xbfb8aa3b, v27
	v_min_f32_e32 v30, 0x42a00000, v30
	v_exp_f32_e32 v30, v30
	s_nop 0
	v_add_f32_e32 v30, 1.0, v30
	v_rcp_f32_e32 v30, v30
	s_nop 0
	v_mul_f32_e32 v27, v27, v30
	v_mul_f32_e32 v30, v26, v27
	v_mov_b32_e32 v26, v28
	v_mov_b32_e32 v27, v32
	v_pk_mul_f32 v[26:27], v[26:27], v[142:143] op_sel_hi:[1,0]
	v_mov_b32_e32 v32, v29
	v_mul_f32_e32 v28, 0xbfb8aa3b, v27
	v_min_f32_e32 v28, 0x42a00000, v28
	v_exp_f32_e32 v28, v28
	s_nop 0
	v_add_f32_e32 v28, 1.0, v28
	v_rcp_f32_e32 v28, v28
	s_nop 0
	v_mul_f32_e32 v27, v27, v28
	v_mul_f32_e32 v28, v26, v27
	v_pk_mul_f32 v[26:27], v[32:33], v[142:143] op_sel_hi:[1,0]
	s_nop 0
	v_mul_f32_e32 v29, 0xbfb8aa3b, v27
	v_min_f32_e32 v29, 0x42a00000, v29
	v_exp_f32_e32 v29, v29
	s_nop 0
	v_add_f32_e32 v29, 1.0, v29
	v_rcp_f32_e32 v29, v29
	s_nop 0
	v_mul_f32_e32 v27, v27, v29
	v_mul_f32_e32 v29, v26, v27
	v_mov_b32_e32 v26, v18
	v_mov_b32_e32 v27, v22
	v_pk_mul_f32 v[26:27], v[26:27], v[142:143] op_sel_hi:[1,0]
	v_mov_b32_e32 v22, v19
	v_mul_f32_e32 v18, 0xbfb8aa3b, v27
	v_min_f32_e32 v18, 0x42a00000, v18
	v_exp_f32_e32 v18, v18
	s_nop 0
	v_add_f32_e32 v18, 1.0, v18
	v_rcp_f32_e32 v18, v18
	s_nop 0
	v_mul_f32_e32 v18, v27, v18
	v_mul_f32_e32 v26, v26, v18
	v_pk_mul_f32 v[18:19], v[22:23], v[142:143] op_sel_hi:[1,0]
	s_nop 0
	v_mul_f32_e32 v22, 0xbfb8aa3b, v19
	v_min_f32_e32 v22, 0x42a00000, v22
	v_exp_f32_e32 v22, v22
	s_nop 0
	v_add_f32_e32 v22, 1.0, v22
	v_rcp_f32_e32 v22, v22
	s_nop 0
	v_mul_f32_e32 v19, v19, v22
	v_mul_f32_e32 v22, v18, v19
	v_mov_b32_e32 v18, v20
	v_mov_b32_e32 v19, v24
	v_pk_mul_f32 v[18:19], v[18:19], v[142:143] op_sel_hi:[1,0]
	v_mov_b32_e32 v24, v21
	v_mul_f32_e32 v20, 0xbfb8aa3b, v19
	v_min_f32_e32 v20, 0x42a00000, v20
	v_exp_f32_e32 v20, v20
	s_nop 0
	v_add_f32_e32 v20, 1.0, v20
	v_rcp_f32_e32 v20, v20
	s_nop 0
	v_mul_f32_e32 v19, v19, v20
	v_mul_f32_e32 v23, v18, v19
	v_pk_mul_f32 v[18:19], v[24:25], v[142:143] op_sel_hi:[1,0]
	s_nop 0
	v_mul_f32_e32 v20, 0xbfb8aa3b, v19
	v_min_f32_e32 v20, 0x42a00000, v20
	v_exp_f32_e32 v20, v20
	s_nop 0
	v_add_f32_e32 v20, 1.0, v20
	v_rcp_f32_e32 v20, v20
	s_nop 0
	v_mul_f32_e32 v19, v19, v20
	v_mul_f32_e32 v21, v18, v19
	v_cvt_pk_bf16_f32 v18, v34, v30
	v_cvt_pk_bf16_f32 v19, v28, v29
	v_cvt_pk_bf16_f32 v20, v26, v22
	v_cvt_pk_bf16_f32 v21, v23, v21
	v_mad_i64_i32 v[22:23], s[2:3], v140, s49, v[114:115]
	v_lshl_add_u64 v[22:23], v[22:23], 0, v[116:117]
	global_store_dwordx4 v[22:23], v[18:21], off
	s_nop 1
	v_mov_b32_e32 v18, v10
	v_mov_b32_e32 v19, v14
	v_pk_mul_f32 v[18:19], v[18:19], v[130:131] op_sel_hi:[1,0]
	v_mov_b32_e32 v14, v11
	v_mul_f32_e32 v10, 0xbfb8aa3b, v19
	v_min_f32_e32 v10, 0x42a00000, v10
	v_exp_f32_e32 v10, v10
	s_nop 0
	v_add_f32_e32 v10, 1.0, v10
	v_rcp_f32_e32 v10, v10
	s_nop 0
	v_mul_f32_e32 v10, v19, v10
	v_mul_f32_e32 v18, v18, v10
	v_pk_mul_f32 v[10:11], v[14:15], v[130:131] op_sel_hi:[1,0]
	s_nop 0
	v_mul_f32_e32 v14, 0xbfb8aa3b, v11
	v_min_f32_e32 v14, 0x42a00000, v14
	v_exp_f32_e32 v14, v14
	s_nop 0
	v_add_f32_e32 v14, 1.0, v14
	v_rcp_f32_e32 v14, v14
	s_nop 0
	v_mul_f32_e32 v11, v11, v14
	v_mul_f32_e32 v14, v10, v11
	v_mov_b32_e32 v10, v12
	v_mov_b32_e32 v11, v16
	v_pk_mul_f32 v[10:11], v[10:11], v[130:131] op_sel_hi:[1,0]
	v_mov_b32_e32 v16, v13
	v_mul_f32_e32 v12, 0xbfb8aa3b, v11
	v_min_f32_e32 v12, 0x42a00000, v12
	v_exp_f32_e32 v12, v12
	s_nop 0
	v_add_f32_e32 v12, 1.0, v12
	v_rcp_f32_e32 v12, v12
	s_nop 0
	v_mul_f32_e32 v11, v11, v12
	v_mul_f32_e32 v12, v10, v11
	v_pk_mul_f32 v[10:11], v[16:17], v[130:131] op_sel_hi:[1,0]
	s_nop 0
	v_mul_f32_e32 v13, 0xbfb8aa3b, v11
	v_min_f32_e32 v13, 0x42a00000, v13
	v_exp_f32_e32 v13, v13
	s_nop 0
	v_add_f32_e32 v13, 1.0, v13
	v_rcp_f32_e32 v13, v13
	s_nop 0
	v_mul_f32_e32 v11, v11, v13
	v_mul_f32_e32 v13, v10, v11
	v_mov_b32_e32 v10, v2
	v_mov_b32_e32 v11, v6
	v_pk_mul_f32 v[10:11], v[10:11], v[130:131] op_sel_hi:[1,0]
	v_mov_b32_e32 v6, v3
	v_mul_f32_e32 v2, 0xbfb8aa3b, v11
	v_min_f32_e32 v2, 0x42a00000, v2
	v_exp_f32_e32 v2, v2
	s_nop 0
	v_add_f32_e32 v2, 1.0, v2
	v_rcp_f32_e32 v2, v2
	s_nop 0
	v_mul_f32_e32 v2, v11, v2
	v_mul_f32_e32 v10, v10, v2
	v_pk_mul_f32 v[2:3], v[6:7], v[130:131] op_sel_hi:[1,0]
	s_nop 0
	v_mul_f32_e32 v6, 0xbfb8aa3b, v3
	v_min_f32_e32 v6, 0x42a00000, v6
	v_exp_f32_e32 v6, v6
	s_nop 0
	v_add_f32_e32 v6, 1.0, v6
	v_rcp_f32_e32 v6, v6
	s_nop 0
	v_mul_f32_e32 v3, v3, v6
	v_mul_f32_e32 v6, v2, v3
	v_mov_b32_e32 v2, v4
	v_mov_b32_e32 v3, v8
	v_pk_mul_f32 v[2:3], v[2:3], v[130:131] op_sel_hi:[1,0]
	v_mov_b32_e32 v8, v5
	v_mul_f32_e32 v4, 0xbfb8aa3b, v3
	v_min_f32_e32 v4, 0x42a00000, v4
	v_exp_f32_e32 v4, v4
	s_nop 0
	v_add_f32_e32 v4, 1.0, v4
	v_rcp_f32_e32 v4, v4
	s_nop 0
	v_mul_f32_e32 v3, v3, v4
	v_mul_f32_e32 v7, v2, v3
	v_pk_mul_f32 v[2:3], v[8:9], v[130:131] op_sel_hi:[1,0]
	s_nop 0
	v_mul_f32_e32 v4, 0xbfb8aa3b, v3
	v_min_f32_e32 v4, 0x42a00000, v4
	v_exp_f32_e32 v4, v4
	s_nop 0
	v_add_f32_e32 v4, 1.0, v4
	v_rcp_f32_e32 v4, v4
	s_nop 0
	v_mul_f32_e32 v3, v3, v4
	v_mul_f32_e32 v5, v2, v3
	v_cvt_pk_bf16_f32 v2, v18, v14
	v_cvt_pk_bf16_f32 v3, v12, v13
	v_cvt_pk_bf16_f32 v4, v10, v6
	v_cvt_pk_bf16_f32 v5, v7, v5
	v_mad_i64_i32 v[6:7], s[2:3], v138, s49, v[114:115]
	v_lshl_add_u64 v[6:7], v[6:7], 0, v[116:117]
	global_store_dwordx4 v[6:7], v[2:5], off
	s_cbranch_vccnz .LBB0_701
	s_andn2_b64 vcc, exec, s[16:17]
	s_cbranch_vccnz .LBB0_700
	s_barrier
	s_branch .LBB0_700
